# speedup vs baseline: 1.0041x; 1.0041x over previous
; #define PG8_BAR __builtin_amdgcn_s_barrier()
; template <class Epi, class Sched>
; __device__ __forceinline__ void gemm_phase(const int tid, LAS unsigned char* lds, const Gemm g, const Sched& S, const Epi& E) {
;     ...
;         const bool has_next = S.next(ui + 1, nxt);
;         const char* nA = has_next ? (const char*)g.A + (size_t)nxt.pm * tstep : cA; const char* nB = has_next ? (const char*)g.Bt + (size_t)nxt.pn * tstep : cB;
;         for (int t = 0; t < nt; t += 2) {
;             const bool last = (t == nt - 2);
;             const char* a1 = cA + (size_t)(t + 1) * kstep;
;             const char* a2 = last ? nA : cA + (size_t)(t + 2) * kstep; const char* b2 = last ? nB : cB + (size_t)(t + 2) * kstep;
;             const char* a3 = a2 + kstep; const char* b3 = b2 + kstep;
;             if (last && has_next) S.a_ready(nxt);
;             PG8_LDB(B0, 0, 0); PG8_LDB(B1, 0, 1); PG8_SCHED; PG8_LDA(At, 0, 0); PG8_STAGE(PG8_SA(1, 1), a1 + hstep, voffA);
;             PG8_WAIT_V(8); PG8_WAIT_L(0); PG8_BAR; PG8_MMA(0, 0, At, B0); PG8_MMA(0, 1, At, B1); PG8_BAR; PG8_SCHED;
;             PG8_LDA(At, 0, 1); PG8_STAGE(PG8_SB(0, 0), b2, voffB); PG8_STAGE(PG8_SB(0, 1), b2 + hstep, voffB); PG8_STAGE(PG8_SA(0, 0), a2, voffA);
;             PG8_WAIT_V(8); PG8_WAIT_L(0); PG8_BAR; PG8_MMA(1, 0, At, B0); PG8_MMA(1, 1, At, B1); PG8_BAR; PG8_SCHED;
;             PG8_LDB(B0, 1, 0); PG8_LDB(B1, 1, 1); PG8_SCHED; PG8_LDA(At, 1, 0); PG8_STAGE(PG8_SA(0, 1), a2 + hstep, voffA);
;             PG8_WAIT_V(8); PG8_WAIT_L(0); PG8_BAR; PG8_MMA(0, 0, At, B0); PG8_MMA(0, 1, At, B1); PG8_BAR; PG8_SCHED;
;             PG8_LDA(At, 1, 1); PG8_STAGE(PG8_SB(1, 0), b3, voffB); PG8_STAGE(PG8_SB(1, 1), b3 + hstep, voffB); PG8_STAGE(PG8_SA(1, 0), a3, voffA);
;             PG8_WAIT_V(8); PG8_WAIT_L(0); PG8_BAR; PG8_MMA(1, 0, At, B0); PG8_MMA(1, 1, At, B1); PG8_BAR; PG8_SCHED;
;         }
;         if (wr == 0) PG8_BAR;
;         asm volatile("s_nop 7\n\ts_nop 7" ::: "memory");
;         E(acc, cur, wr, wc, fr, fq); S.done(cur);
;         if (!has_next) break;
; #pragma unroll
;         for (int a = 0; a < 2; ++a)
; #pragma unroll
;             for (int b = 0; b < 2; ++b)
; #pragma unroll
;                 for (int m = 0; m < 4; ++m)
; #pragma unroll
;                     for (int n = 0; n < 2; ++n) acc[a][b][m][n] = (f32x4){0.f, 0.f, 0.f, 0.f};
;         cur = nxt; cA = nA; cB = nB; ++ui;
.LBB0_49:
	s_ashr_i32 s15, s14, 31
	s_lshl_b64 s[16:17], s[14:15], 20
	s_add_u32 s16, s41, s16
	s_addc_u32 s17, s55, s17
	s_and_b64 s[18:19], s[0:1], exec
	s_cselect_b32 s15, s17, s23
	s_cselect_b32 s66, s16, s22
	s_ashr_i32 s13, s12, 31
	s_lshl_b64 s[18:19], s[12:13], 20
	v_readlane_b32 s13, v243, 16
	s_add_u32 s18, s13, s18
	v_readlane_b32 s13, v243, 17
	s_addc_u32 s19, s13, s19
	s_and_b64 s[26:27], s[0:1], exec
	s_cselect_b32 s13, s19, s25
	s_cselect_b32 s67, s18, s24
	s_add_u32 s22, s22, 0x80080
	s_addc_u32 s23, s23, 0
	s_add_u32 s68, s24, 0x100
	v_mov_b32_e32 v0, 0
	s_addc_u32 s69, s25, 0
	s_mov_b32 s70, -2
	v_mov_b32_e32 v1, 0
	v_mov_b64_e32 v[2:3], 0
	v_mov_b64_e32 v[4:5], 0
	v_mov_b64_e32 v[6:7], 0
	v_mov_b64_e32 v[8:9], 0
	v_mov_b64_e32 v[10:11], 0
	v_mov_b64_e32 v[12:13], 0
	v_mov_b64_e32 v[14:15], 0
	v_mov_b64_e32 v[16:17], 0
	v_mov_b64_e32 v[18:19], 0
	v_mov_b64_e32 v[20:21], 0
	v_mov_b64_e32 v[22:23], 0
	v_mov_b64_e32 v[24:25], 0
	v_mov_b64_e32 v[26:27], 0
	v_mov_b64_e32 v[28:29], 0
	v_mov_b64_e32 v[30:31], 0
	v_mov_b64_e32 v[32:33], 0
	v_mov_b64_e32 v[34:35], 0
	v_mov_b64_e32 v[36:37], 0
	v_mov_b64_e32 v[38:39], 0
	v_mov_b64_e32 v[40:41], 0
	v_mov_b64_e32 v[42:43], 0
	v_mov_b64_e32 v[44:45], 0
	v_mov_b64_e32 v[46:47], 0
	v_mov_b64_e32 v[48:49], 0
	v_mov_b64_e32 v[50:51], 0
	v_mov_b64_e32 v[52:53], 0
	v_mov_b64_e32 v[54:55], 0
	v_mov_b64_e32 v[56:57], 0
	v_mov_b64_e32 v[58:59], 0
	v_mov_b64_e32 v[60:61], 0
	v_mov_b64_e32 v[62:63], 0
	v_mov_b64_e32 v[64:65], 0
	v_mov_b64_e32 v[66:67], 0
	v_mov_b64_e32 v[68:69], 0
	v_mov_b64_e32 v[70:71], 0
	v_mov_b64_e32 v[72:73], 0
	v_mov_b64_e32 v[74:75], 0
	v_mov_b64_e32 v[76:77], 0
	v_mov_b64_e32 v[78:79], 0
	v_mov_b64_e32 v[80:81], 0
	v_mov_b64_e32 v[82:83], 0
	v_mov_b64_e32 v[84:85], 0
	v_mov_b64_e32 v[86:87], 0
	v_mov_b64_e32 v[88:89], 0
	v_mov_b64_e32 v[90:91], 0
	v_mov_b64_e32 v[92:93], 0
	v_mov_b64_e32 v[94:95], 0
	v_mov_b64_e32 v[96:97], 0
	v_mov_b64_e32 v[98:99], 0
	v_mov_b64_e32 v[100:101], 0
	v_mov_b64_e32 v[102:103], 0
	v_mov_b64_e32 v[104:105], 0
	v_mov_b64_e32 v[106:107], 0
	v_mov_b64_e32 v[108:109], 0
	v_mov_b64_e32 v[110:111], 0
	v_mov_b64_e32 v[112:113], 0
	v_mov_b64_e32 v[114:115], 0
	v_mov_b64_e32 v[116:117], 0
	v_mov_b64_e32 v[118:119], 0
	v_mov_b64_e32 v[120:121], 0
	v_mov_b64_e32 v[122:123], 0
	v_mov_b64_e32 v[124:125], 0
	v_mov_b64_e32 v[126:127], 0

; __device__ __forceinline__ void unpack8(const u32x4 w, float* f) { f[0] = bflo(w.x); f[1] = bfhi(w.x); f[2] = bflo(w.y); f[3] = bfhi(w.y); f[4] = bflo(w.z); f[5] = bfhi(w.z); f[6] = bflo(w.w); f[7] = bfhi(w.w); }
; __device__ __forceinline__ void gmlp_fast(KArgs ap, int l, LAS unsigned char* lds, const Ctx cx) {
;     ...
;         u32x4 raw[8];
; #pragma unroll
;         for (int j = 0; j < 8; ++j) raw[j] = *(const u32x4*)(z + (t0 + wave * 16 + i0 + j) * DIN + ZGV + lane * 8);
; #pragma unroll
;         for (int j = 0; j < 8; ++j) { const int s = wave * 16 + i0 + j;
;             float v[8]; unpack8(raw[j], v);
;             float sm = 0.f;
; #pragma unroll
;             for (int e = 0; e < 8; ++e) { v[e] = gelu_tanh(v[e]); sm += v[e]; }
;             const float mean = wave_sum(sm) * (1.0f / 512.f);
;             float s2 = 0.f;
; #pragma unroll
;             for (int e = 0; e < 8; ++e) { const float d = v[e] - mean; s2 += d * d; }
;             const float rstd = 1.0f / sqrtf(wave_sum(s2) * (1.0f / 512.f) + EPS);
;             if (lane == 0) { ST[2 * s] = mean; ST[2 * s + 1] = rstd; } }
.LBB0_143:
	s_or_b32 s1, s13, s0
	s_mul_hi_u32 s24, s1, 0x1600
	s_add_i32 s25, s24, s41
	s_mulk_i32 s1, 0x1600
	s_add_u32 s24, s16, s1
	s_addc_u32 s25, s17, s25
	v_lshl_add_u64 v[0:1], s[24:25], 0, v[152:153]
	s_movk_i32 s1, 0x1000
	s_waitcnt lgkmcnt(0)
	v_add_co_u32_e32 v2, vcc, s1, v0
	s_movk_i32 s1, 0x2000
	s_nop 0
	v_addc_co_u32_e32 v3, vcc, 0, v1, vcc
	global_load_dwordx4 v[8:11], v[2:3], off offset:512
	v_add_co_u32_e32 v2, vcc, s1, v0
	s_movk_i32 s1, 0x3000
	s_nop 0
	v_addc_co_u32_e32 v3, vcc, 0, v1, vcc
	v_add_co_u32_e32 v4, vcc, s1, v0
	s_movk_i32 s1, 0x5000
	s_nop 0
	v_addc_co_u32_e32 v5, vcc, 0, v1, vcc
	global_load_dwordx4 v[24:27], v[2:3], off offset:2048
	v_add_co_u32_e32 v2, vcc, s1, v0
	s_movk_i32 s1, 0x6000
	s_nop 0
	v_addc_co_u32_e32 v3, vcc, 0, v1, vcc
	v_add_co_u32_e32 v6, vcc, s1, v0
	s_mov_b32 s1, 0x8000
	s_nop 0
	v_addc_co_u32_e32 v7, vcc, 0, v1, vcc
	global_load_dwordx4 v[20:23], v[4:5], off offset:3584
	global_load_dwordx4 v[16:19], v[2:3], off offset:1024
	v_add_co_u32_e32 v4, vcc, s1, v0
	s_mov_b32 s1, 0x9000
	s_nop 0
	v_addc_co_u32_e32 v5, vcc, 0, v1, vcc
	v_add_co_u32_e32 v2, vcc, s1, v0
	s_mov_b32 s1, 0xa000
	s_nop 0
	v_addc_co_u32_e32 v3, vcc, 0, v1, vcc
	v_add_co_u32_e32 v0, vcc, s1, v0
	global_load_dwordx4 v[12:15], v[6:7], off offset:2560
	s_nop 0
	global_load_dwordx4 v[4:7], v[4:5], off
	v_addc_co_u32_e32 v1, vcc, 0, v1, vcc
	s_or_b32 s56, s0, s26
	s_waitcnt vmcnt(5)
	v_lshlrev_b32_e32 v28, 16, v8
	v_mul_f32_e32 v32, 0x3d372713, v28
	v_mul_f32_e32 v32, v32, v28
	v_mul_f32_e32 v33, 0.5, v28
	v_fma_f32 v28, v32, v28, v28
	v_mul_f32_e32 v28, 0x3f4c422a, v28
	v_add_f32_e32 v28, v28, v28
	v_mul_f32_e32 v28, 0x3fb8aa3b, v28
	v_exp_f32_e32 v28, v28
	v_and_b32_e32 v8, 0xffff0000, v8
	v_lshlrev_b32_e32 v30, 16, v10
	v_mul_f32_e32 v34, 0x3d372713, v8
	v_add_f32_e32 v28, 1.0, v28
	v_rcp_f32_e32 v28, v28
	v_mul_f32_e32 v39, 0x3d372713, v30
	v_lshlrev_b32_e32 v29, 16, v9
	v_mul_f32_e32 v34, v34, v8
	v_mul_f32_e32 v39, v39, v30
	v_mul_f32_e32 v35, 0.5, v8
	v_mul_f32_e32 v36, 0x3d372713, v29
	v_fma_f32 v8, v34, v8, v8
	v_fma_f32 v34, v39, v30, v30
	v_mul_f32_e32 v36, v36, v29
	v_mul_f32_e32 v34, 0x3f4c422a, v34
	v_fma_f32 v28, v28, -2.0, 1.0
	v_mul_f32_e32 v37, 0.5, v29
	v_fma_f32 v29, v36, v29, v29
	v_add_f32_e32 v36, 1.0, v28
	v_add_f32_e32 v28, v34, v34
	v_mul_f32_e32 v28, 0x3fb8aa3b, v28
	v_exp_f32_e32 v28, v28
	v_and_b32_e32 v9, 0xffff0000, v9
	v_mul_f32_e32 v38, 0x3d372713, v9
	v_and_b32_e32 v10, 0xffff0000, v10
	v_mul_f32_e32 v38, v38, v9
	v_fma_f32 v32, v38, v9, v9
	v_mul_f32_e32 v34, 0.5, v9
	v_add_f32_e32 v9, 1.0, v28
	v_mul_f32_e32 v28, 0x3d372713, v10
	v_mul_f32_e32 v28, v28, v10
	v_fma_f32 v28, v28, v10, v10
	v_mul_f32_e32 v28, 0x3f4c422a, v28
	v_add_f32_e32 v28, v28, v28
	v_rcp_f32_e32 v9, v9
	v_mul_f32_e32 v28, 0x3fb8aa3b, v28
	v_exp_f32_e32 v28, v28
	v_lshlrev_b32_e32 v31, 16, v11
	v_fma_f32 v9, v9, -2.0, 1.0
	v_add_f32_e32 v39, 1.0, v9
	v_add_f32_e32 v9, 1.0, v28
	v_mul_f32_e32 v28, 0x3d372713, v31
	v_mul_f32_e32 v28, v28, v31
	v_fma_f32 v28, v28, v31, v31
	v_mul_f32_e32 v28, 0x3f4c422a, v28
	v_add_f32_e32 v28, v28, v28
	v_mul_f32_e32 v28, 0x3fb8aa3b, v28
	v_exp_f32_e32 v28, v28
	v_mul_f32_e32 v8, 0x3f4c422a, v8
	v_mul_f32_e32 v29, 0x3f4c422a, v29
	v_add_f32_e32 v8, v8, v8
	v_and_b32_e32 v11, 0xffff0000, v11
	v_mul_f32_e32 v32, 0x3f4c422a, v32
	v_add_f32_e32 v29, v29, v29
	v_mul_f32_e32 v8, 0x3fb8aa3b, v8
	v_add_f32_e32 v32, v32, v32
	v_mul_f32_e32 v29, 0x3fb8aa3b, v29
	v_exp_f32_e32 v8, v8
	v_mul_f32_e32 v40, 0.5, v10
	v_add_f32_e32 v10, 1.0, v28
	v_mul_f32_e32 v28, 0x3d372713, v11
	v_mul_f32_e32 v32, 0x3fb8aa3b, v32
	v_exp_f32_e32 v29, v29
	v_mul_f32_e32 v28, v28, v11
	v_exp_f32_e32 v32, v32
	v_fma_f32 v28, v28, v11, v11
	v_mul_f32_e32 v28, 0x3f4c422a, v28
	v_add_f32_e32 v8, 1.0, v8
	v_add_f32_e32 v28, v28, v28
	v_add_f32_e32 v29, 1.0, v29
	v_rcp_f32_e32 v8, v8
	v_rcp_f32_e32 v9, v9
	v_mul_f32_e32 v28, 0x3fb8aa3b, v28
	v_add_f32_e32 v32, 1.0, v32
	v_rcp_f32_e32 v29, v29
	v_rcp_f32_e32 v10, v10
	v_exp_f32_e32 v28, v28
	v_rcp_f32_e32 v32, v32
	v_fma_f32 v8, v8, -2.0, 1.0
	v_fma_f32 v9, v9, -2.0, 1.0
	v_fma_f32 v29, v29, -2.0, 1.0
	v_add_f32_e32 v38, 1.0, v8
	v_fma_f32 v8, v33, v36, 0
	v_add_f32_e32 v41, 1.0, v9
	v_fma_f32 v9, v10, -2.0, 1.0
	v_add_f32_e32 v10, 1.0, v28
	v_fma_f32 v32, v32, -2.0, 1.0
	v_add_f32_e32 v29, 1.0, v29
	v_fmac_f32_e32 v8, v35, v38
	v_rcp_f32_e32 v10, v10
	v_fmac_f32_e32 v8, v37, v29
	v_add_f32_e32 v32, 1.0, v32
	v_fmac_f32_e32 v8, v34, v32
	v_mul_f32_e32 v30, 0.5, v30
	v_fmac_f32_e32 v8, v30, v39
	v_fmac_f32_e32 v8, v40, v41
	v_mul_f32_e32 v31, 0.5, v31
	v_add_f32_e32 v42, 1.0, v9
	v_fma_f32 v9, v10, -2.0, 1.0
	v_fmac_f32_e32 v8, v31, v42
	v_mul_f32_e32 v43, 0.5, v11
	v_add_f32_e32 v44, 1.0, v9
	v_fmac_f32_e32 v8, v43, v44
	s_nop 1
	v_add_f32_dpp v28, v8, v8 quad_perm:[1,0,3,2] row_mask:0xf bank_mask:0xf
	s_nop 1
	v_add_f32_dpp v28, v28, v28 quad_perm:[2,3,0,1] row_mask:0xf bank_mask:0xf
	s_nop 1
	v_add_f32_dpp v28, v28, v28 row_half_mirror row_mask:0xf bank_mask:0xf
	s_nop 1
	v_add_f32_dpp v28, v28, v28 row_mirror row_mask:0xf bank_mask:0xf
	s_nop 1
	v_add_f32_dpp v28, v28, v28 row_bcast:15 row_mask:0xa bank_mask:0xf
	s_nop 1
	v_add_f32_dpp v28, v28, v28 row_bcast:31 row_mask:0xc bank_mask:0xf
	s_nop 1
	v_readlane_b32 s58, v28, 63
	s_nop 1
	v_mov_b32_e32 v28, s58
	global_load_dwordx4 v[8:11], v[2:3], off offset:1536
	s_nop 0
	global_load_dwordx4 v[0:3], v[0:1], off offset:3072
	v_mul_f32_e32 v28, 0x3b000000, v28
	v_fma_f32 v35, v35, v38, -v28
	v_fma_f32 v33, v33, v36, -v28
	v_mul_f32_e32 v35, v35, v35
	v_fmac_f32_e32 v35, v33, v33
	v_fma_f32 v29, v37, v29, -v28
	v_fmac_f32_e32 v35, v29, v29
	v_fma_f32 v29, v34, v32, -v28
	v_fmac_f32_e32 v35, v29, v29
	v_fma_f32 v29, v30, v39, -v28
	v_fmac_f32_e32 v35, v29, v29
	v_fma_f32 v29, v40, v41, -v28
	v_fmac_f32_e32 v35, v29, v29
	v_fma_f32 v29, v31, v42, -v28
	v_fmac_f32_e32 v35, v29, v29
	v_fma_f32 v29, v43, v44, -v28
	v_fmac_f32_e32 v35, v29, v29
	s_nop 1
	v_add_f32_dpp v29, v35, v35 quad_perm:[1,0,3,2] row_mask:0xf bank_mask:0xf
	s_nop 1
	v_add_f32_dpp v29, v29, v29 quad_perm:[2,3,0,1] row_mask:0xf bank_mask:0xf
	s_nop 1
	v_add_f32_dpp v29, v29, v29 row_half_mirror row_mask:0xf bank_mask:0xf
	s_nop 1
	v_add_f32_dpp v29, v29, v29 row_mirror row_mask:0xf bank_mask:0xf
	s_nop 1
	v_add_f32_dpp v29, v29, v29 row_bcast:15 row_mask:0xa bank_mask:0xf
	s_nop 1
	v_add_f32_dpp v29, v29, v29 row_bcast:31 row_mask:0xc bank_mask:0xf
	s_nop 1
	v_readlane_b32 s58, v29, 63
	s_nop 1
	v_mov_b32_e32 v29, s58
	s_and_saveexec_b64 s[24:25], s[6:7]
	s_cbranch_execz .LBB0_145
; __device__ __forceinline__ void unpack8(const u32x4 w, float* f) { f[0] = bflo(w.x); f[1] = bfhi(w.x); f[2] = bflo(w.y); f[3] = bfhi(w.y); f[4] = bflo(w.z); f[5] = bfhi(w.z); f[6] = bflo(w.w); f[7] = bfhi(w.w); }
; __device__ __forceinline__ void gmlp_fast(KArgs ap, int l, LAS unsigned char* lds, const Ctx cx) {
;     ...
;         for (int j = 0; j < 8; ++j) { const int s = wave * 16 + i0 + j;
;             float v[8]; unpack8(raw[j], v);
;             float sm = 0.f;
; #pragma unroll
;             for (int e = 0; e < 8; ++e) { v[e] = gelu_tanh(v[e]); sm += v[e]; }
;             const float mean = wave_sum(sm) * (1.0f / 512.f);
;             float s2 = 0.f;
; #pragma unroll
;             for (int e = 0; e < 8; ++e) { const float d = v[e] - mean; s2 += d * d; }
;             const float rstd = 1.0f / sqrtf(wave_sum(s2) * (1.0f / 512.f) + EPS);
;             if (lane == 0) { ST[2 * s] = mean; ST[2 * s + 1] = rstd; } }
	v_fmamk_f32 v29, v29, 0x3b000000, v194
	s_mov_b32 s0, 0xf800000
	v_mul_f32_e32 v30, 0x4f800000, v29
	v_cmp_gt_f32_e32 vcc, s0, v29
	s_nop 1
	v_cndmask_b32_e32 v29, v29, v30, vcc
	v_sqrt_f32_e32 v30, v29
	s_nop 0
	v_add_u32_e32 v31, -1, v30
	v_fma_f32 v33, -v31, v30, v29
	v_add_u32_e32 v32, 1, v30
	v_cmp_ge_f32_e64 s[0:1], 0, v33
	s_nop 1
	v_cndmask_b32_e64 v31, v30, v31, s[0:1]
	v_fma_f32 v30, -v32, v30, v29
	v_cmp_lt_f32_e64 s[0:1], 0, v30
	s_nop 1
	v_cndmask_b32_e64 v30, v31, v32, s[0:1]
	v_mul_f32_e32 v31, 0x37800000, v30
	v_cndmask_b32_e32 v30, v30, v31, vcc
	v_cmp_class_f32_e32 vcc, v29, v195
	s_nop 1
	v_cndmask_b32_e32 v29, v30, v29, vcc
	v_div_scale_f32 v30, s[0:1], v29, v29, 1.0
	v_rcp_f32_e32 v31, v30
	s_lshl_b32 s0, s56, 3
	s_add_i32 s0, s0, 0
	s_add_i32 s0, s0, 0x11000
	v_fma_f32 v32, -v30, v31, 1.0
	v_fmac_f32_e32 v31, v32, v31
	v_div_scale_f32 v32, vcc, 1.0, v29, 1.0
	v_mul_f32_e32 v33, v32, v31
	v_fma_f32 v34, -v30, v33, v32
	v_fmac_f32_e32 v33, v34, v31
	v_fma_f32 v30, -v30, v33, v32
	v_div_fmas_f32 v30, v30, v31, v33
	v_div_fixup_f32 v29, v30, v29, 1.0
	v_mov_b32_e32 v30, s0
	ds_write_b64 v30, v[28:29]
.LBB0_145:
	s_or_b64 exec, exec, s[24:25]
	s_waitcnt vmcnt(6)
	v_lshlrev_b32_e32 v29, 16, v25
	v_mul_f32_e32 v34, 0x3d372713, v29
	v_mul_f32_e32 v34, v34, v29
	v_fma_f32 v34, v34, v29, v29
	v_mul_f32_e32 v34, 0x3f4c422a, v34
	v_add_f32_e32 v34, v34, v34
	v_mul_f32_e32 v34, 0x3fb8aa3b, v34
	v_exp_f32_e32 v34, v34
	v_lshlrev_b32_e32 v28, 16, v24
	v_and_b32_e32 v24, 0xffff0000, v24
	v_mul_f32_e32 v33, 0x3d372713, v24
	v_and_b32_e32 v25, 0xffff0000, v25
	v_mul_f32_e32 v33, v33, v24
	v_fma_f32 v33, v33, v24, v24
	v_mul_f32_e32 v36, 0.5, v24
	v_add_f32_e32 v24, 1.0, v34
	v_mul_f32_e32 v34, 0x3d372713, v25
	v_mul_f32_e32 v34, v34, v25
	v_fma_f32 v34, v34, v25, v25
	v_mul_f32_e32 v34, 0x3f4c422a, v34
	v_add_f32_e32 v34, v34, v34
	v_mul_f32_e32 v34, 0x3fb8aa3b, v34
	v_exp_f32_e32 v34, v34
	v_rcp_f32_e32 v24, v24
	s_waitcnt lgkmcnt(0)
	v_lshlrev_b32_e32 v30, 16, v26
	v_and_b32_e32 v26, 0xffff0000, v26
	v_add_f32_e32 v34, 1.0, v34
	v_rcp_f32_e32 v34, v34
	v_fma_f32 v24, v24, -2.0, 1.0
	v_add_f32_e32 v37, 1.0, v24
	v_mul_f32_e32 v31, 0x3d372713, v28
	v_fma_f32 v24, v34, -2.0, 1.0
	v_mul_f32_e32 v34, 0x3d372713, v30
	v_mul_f32_e32 v34, v34, v30
	v_fma_f32 v34, v34, v30, v30
	v_mul_f32_e32 v34, 0x3f4c422a, v34
	v_add_f32_e32 v34, v34, v34
	v_mul_f32_e32 v34, 0x3fb8aa3b, v34
	v_exp_f32_e32 v34, v34
	v_add_f32_e32 v38, 1.0, v24
	v_mul_f32_e32 v31, v31, v28
	v_lshlrev_b32_e32 v32, 16, v27
	v_add_f32_e32 v24, 1.0, v34
	v_mul_f32_e32 v34, 0x3d372713, v26
	v_mul_f32_e32 v34, v34, v26
	v_fma_f32 v34, v34, v26, v26
	v_mul_f32_e32 v34, 0x3f4c422a, v34
	v_add_f32_e32 v34, v34, v34
	v_rcp_f32_e32 v24, v24
	v_mul_f32_e32 v34, 0x3fb8aa3b, v34
	v_exp_f32_e32 v34, v34
	v_fma_f32 v31, v31, v28, v28
	v_fma_f32 v24, v24, -2.0, 1.0
	v_add_f32_e32 v39, 1.0, v24
	v_add_f32_e32 v24, 1.0, v34
	v_mul_f32_e32 v34, 0x3d372713, v32
	v_mul_f32_e32 v31, 0x3f4c422a, v31
	v_mul_f32_e32 v34, v34, v32
	v_add_f32_e32 v31, v31, v31
	v_mul_f32_e32 v33, 0x3f4c422a, v33
	v_fma_f32 v34, v34, v32, v32
	v_mul_f32_e32 v31, 0x3fb8aa3b, v31
	v_add_f32_e32 v33, v33, v33
	v_mul_f32_e32 v34, 0x3f4c422a, v34
	v_exp_f32_e32 v31, v31
	v_and_b32_e32 v27, 0xffff0000, v27
	v_mul_f32_e32 v33, 0x3fb8aa3b, v33
	v_add_f32_e32 v34, v34, v34
	v_exp_f32_e32 v33, v33
	v_mul_f32_e32 v34, 0x3fb8aa3b, v34
	v_mul_f32_e32 v40, 0x3d372713, v27
	v_exp_f32_e32 v34, v34
	v_mul_f32_e32 v40, v40, v27
	v_fma_f32 v40, v40, v27, v27
	v_add_f32_e32 v31, 1.0, v31
	v_mul_f32_e32 v40, 0x3f4c422a, v40
	v_rcp_f32_e32 v31, v31
	v_add_f32_e32 v33, 1.0, v33
	v_add_f32_e32 v40, v40, v40
	v_rcp_f32_e32 v33, v33
	v_rcp_f32_e32 v24, v24
	v_add_f32_e32 v34, 1.0, v34
	v_mul_f32_e32 v40, 0x3fb8aa3b, v40
	v_rcp_f32_e32 v34, v34
	v_exp_f32_e32 v40, v40
	v_fma_f32 v31, v31, -2.0, 1.0
	v_mul_f32_e32 v28, 0.5, v28
	v_add_f32_e32 v31, 1.0, v31
	v_fma_f32 v33, v33, -2.0, 1.0
	v_fma_f32 v24, v24, -2.0, 1.0
	v_fma_f32 v35, v28, v31, 0
	v_add_f32_e32 v33, 1.0, v33
	v_add_f32_e32 v41, 1.0, v24
	v_fma_f32 v24, v34, -2.0, 1.0
	v_add_f32_e32 v34, 1.0, v40
	v_fmac_f32_e32 v35, v36, v33
	v_mul_f32_e32 v29, 0.5, v29
	v_rcp_f32_e32 v34, v34
	v_fmac_f32_e32 v35, v29, v37
	v_mul_f32_e32 v25, 0.5, v25
	v_fmac_f32_e32 v35, v25, v38
	v_mul_f32_e32 v30, 0.5, v30
	v_fmac_f32_e32 v35, v30, v39
	v_mul_f32_e32 v26, 0.5, v26
	v_fmac_f32_e32 v35, v26, v41
	v_mul_f32_e32 v32, 0.5, v32
	v_add_f32_e32 v40, 1.0, v24
	v_fma_f32 v24, v34, -2.0, 1.0
	v_fmac_f32_e32 v35, v32, v40
	v_mul_f32_e32 v27, 0.5, v27
	v_add_f32_e32 v34, 1.0, v24
	v_fmac_f32_e32 v35, v27, v34
	s_nop 1
	v_add_f32_dpp v24, v35, v35 quad_perm:[1,0,3,2] row_mask:0xf bank_mask:0xf
	s_nop 1
	v_add_f32_dpp v24, v24, v24 quad_perm:[2,3,0,1] row_mask:0xf bank_mask:0xf
	s_nop 1
	v_add_f32_dpp v24, v24, v24 row_half_mirror row_mask:0xf bank_mask:0xf
	s_nop 1
	v_add_f32_dpp v24, v24, v24 row_mirror row_mask:0xf bank_mask:0xf
	s_nop 1
	v_add_f32_dpp v24, v24, v24 row_bcast:15 row_mask:0xa bank_mask:0xf
	s_nop 1
	v_add_f32_dpp v24, v24, v24 row_bcast:31 row_mask:0xc bank_mask:0xf
	s_nop 1
	v_readlane_b32 s58, v24, 63
	s_nop 1
	v_mov_b32_e32 v24, s58
	v_mul_f32_e32 v24, 0x3b000000, v24
	v_fma_f32 v28, v28, v31, -v24
	v_fma_f32 v31, v36, v33, -v24
	v_mul_f32_e32 v31, v31, v31
	v_fmac_f32_e32 v31, v28, v28
	v_fma_f32 v28, v29, v37, -v24
	v_fmac_f32_e32 v31, v28, v28
	v_fma_f32 v25, v25, v38, -v24
	v_fmac_f32_e32 v31, v25, v25
	v_fma_f32 v25, v30, v39, -v24
	v_fmac_f32_e32 v31, v25, v25
	v_fma_f32 v25, v26, v41, -v24
	v_fmac_f32_e32 v31, v25, v25
	v_fma_f32 v25, v32, v40, -v24
	v_fmac_f32_e32 v31, v25, v25
	v_fma_f32 v25, v27, v34, -v24
	v_fmac_f32_e32 v31, v25, v25
	s_nop 1
	v_add_f32_dpp v25, v31, v31 quad_perm:[1,0,3,2] row_mask:0xf bank_mask:0xf
	s_nop 1
	v_add_f32_dpp v25, v25, v25 quad_perm:[2,3,0,1] row_mask:0xf bank_mask:0xf
	s_nop 1
	v_add_f32_dpp v25, v25, v25 row_half_mirror row_mask:0xf bank_mask:0xf
	s_nop 1
	v_add_f32_dpp v25, v25, v25 row_mirror row_mask:0xf bank_mask:0xf
	s_nop 1
	v_add_f32_dpp v25, v25, v25 row_bcast:15 row_mask:0xa bank_mask:0xf
	s_nop 1
	v_add_f32_dpp v25, v25, v25 row_bcast:31 row_mask:0xc bank_mask:0xf
	s_nop 1
	v_readlane_b32 s58, v25, 63
	s_nop 1
	v_mov_b32_e32 v25, s58
	s_and_saveexec_b64 s[24:25], s[6:7]
	s_cbranch_execz .LBB0_147
; __device__ __forceinline__ void unpack8(const u32x4 w, float* f) { f[0] = bflo(w.x); f[1] = bfhi(w.x); f[2] = bflo(w.y); f[3] = bfhi(w.y); f[4] = bflo(w.z); f[5] = bfhi(w.z); f[6] = bflo(w.w); f[7] = bfhi(w.w); }
; __device__ __forceinline__ void gmlp_fast(KArgs ap, int l, LAS unsigned char* lds, const Ctx cx) {
;     ...
;         for (int j = 0; j < 8; ++j) { const int s = wave * 16 + i0 + j;
;             float v[8]; unpack8(raw[j], v);
;             float sm = 0.f;
; #pragma unroll
;             for (int e = 0; e < 8; ++e) { v[e] = gelu_tanh(v[e]); sm += v[e]; }
;             const float mean = wave_sum(sm) * (1.0f / 512.f);
;             float s2 = 0.f;
; #pragma unroll
;             for (int e = 0; e < 8; ++e) { const float d = v[e] - mean; s2 += d * d; }
;             const float rstd = 1.0f / sqrtf(wave_sum(s2) * (1.0f / 512.f) + EPS);
;             if (lane == 0) { ST[2 * s] = mean; ST[2 * s + 1] = rstd; } }
	v_fmamk_f32 v25, v25, 0x3b000000, v194
	s_mov_b32 s0, 0xf800000
	v_mul_f32_e32 v26, 0x4f800000, v25
	v_cmp_gt_f32_e32 vcc, s0, v25
	s_nop 1
	v_cndmask_b32_e32 v25, v25, v26, vcc
	v_sqrt_f32_e32 v26, v25
	s_nop 0
	v_add_u32_e32 v27, -1, v26
	v_fma_f32 v29, -v27, v26, v25
	v_add_u32_e32 v28, 1, v26
	v_cmp_ge_f32_e64 s[0:1], 0, v29
	s_nop 1
	v_cndmask_b32_e64 v27, v26, v27, s[0:1]
	v_fma_f32 v26, -v28, v26, v25
	v_cmp_lt_f32_e64 s[0:1], 0, v26
	s_nop 1
	v_cndmask_b32_e64 v26, v27, v28, s[0:1]
	v_mul_f32_e32 v27, 0x37800000, v26
	v_cndmask_b32_e32 v26, v26, v27, vcc
	v_cmp_class_f32_e32 vcc, v25, v195
	s_nop 1
	v_cndmask_b32_e32 v25, v26, v25, vcc
	v_div_scale_f32 v26, s[0:1], v25, v25, 1.0
	v_rcp_f32_e32 v27, v26
	s_lshl_b32 s0, s56, 3
	s_add_i32 s0, s0, 0
	s_add_i32 s0, s0, 0x11008
	v_fma_f32 v28, -v26, v27, 1.0
	v_fmac_f32_e32 v27, v28, v27
	v_div_scale_f32 v28, vcc, 1.0, v25, 1.0
	v_mul_f32_e32 v29, v28, v27
	v_fma_f32 v30, -v26, v29, v28
	v_fmac_f32_e32 v29, v30, v27
	v_fma_f32 v26, -v26, v29, v28
	v_div_fmas_f32 v26, v26, v27, v29
	v_div_fixup_f32 v25, v26, v25, 1.0
	v_mov_b32_e32 v26, s0
	ds_write_b64 v26, v[24:25]
.LBB0_147:
	s_or_b64 exec, exec, s[24:25]
	s_waitcnt vmcnt(5)
	v_lshlrev_b32_e32 v25, 16, v21
	v_mul_f32_e32 v30, 0x3d372713, v25
	v_mul_f32_e32 v30, v30, v25
	v_fma_f32 v30, v30, v25, v25
	v_mul_f32_e32 v30, 0x3f4c422a, v30
	v_add_f32_e32 v30, v30, v30
	v_mul_f32_e32 v30, 0x3fb8aa3b, v30
	v_exp_f32_e32 v30, v30
	v_lshlrev_b32_e32 v24, 16, v20
	v_and_b32_e32 v20, 0xffff0000, v20
	v_mul_f32_e32 v29, 0x3d372713, v20
	v_and_b32_e32 v21, 0xffff0000, v21
	v_mul_f32_e32 v29, v29, v20
	v_fma_f32 v29, v29, v20, v20
	v_mul_f32_e32 v32, 0.5, v20
	v_add_f32_e32 v20, 1.0, v30
	v_mul_f32_e32 v30, 0x3d372713, v21
	v_mul_f32_e32 v30, v30, v21
	v_fma_f32 v30, v30, v21, v21
	v_mul_f32_e32 v30, 0x3f4c422a, v30
	v_add_f32_e32 v30, v30, v30
	v_mul_f32_e32 v30, 0x3fb8aa3b, v30
	v_exp_f32_e32 v30, v30
	v_rcp_f32_e32 v20, v20
	s_waitcnt lgkmcnt(0)
	v_lshlrev_b32_e32 v26, 16, v22
	v_and_b32_e32 v22, 0xffff0000, v22
	v_add_f32_e32 v30, 1.0, v30
	v_rcp_f32_e32 v30, v30
	v_fma_f32 v20, v20, -2.0, 1.0
	v_add_f32_e32 v33, 1.0, v20
	v_mul_f32_e32 v27, 0x3d372713, v24
	v_fma_f32 v20, v30, -2.0, 1.0
	v_mul_f32_e32 v30, 0x3d372713, v26
	v_mul_f32_e32 v30, v30, v26
	v_fma_f32 v30, v30, v26, v26
	v_mul_f32_e32 v30, 0x3f4c422a, v30
	v_add_f32_e32 v30, v30, v30
	v_mul_f32_e32 v30, 0x3fb8aa3b, v30
	v_exp_f32_e32 v30, v30
	v_add_f32_e32 v34, 1.0, v20
	v_mul_f32_e32 v27, v27, v24
	v_lshlrev_b32_e32 v28, 16, v23
	v_add_f32_e32 v20, 1.0, v30
	v_mul_f32_e32 v30, 0x3d372713, v22
	v_mul_f32_e32 v30, v30, v22
	v_fma_f32 v30, v30, v22, v22
	v_mul_f32_e32 v30, 0x3f4c422a, v30
	v_add_f32_e32 v30, v30, v30
	v_rcp_f32_e32 v20, v20
	v_mul_f32_e32 v30, 0x3fb8aa3b, v30
	v_exp_f32_e32 v30, v30
	v_fma_f32 v27, v27, v24, v24
	v_fma_f32 v20, v20, -2.0, 1.0
	v_add_f32_e32 v35, 1.0, v20
	v_add_f32_e32 v20, 1.0, v30
	v_mul_f32_e32 v30, 0x3d372713, v28
	v_mul_f32_e32 v27, 0x3f4c422a, v27
	v_mul_f32_e32 v30, v30, v28
	v_add_f32_e32 v27, v27, v27
	v_mul_f32_e32 v29, 0x3f4c422a, v29
	v_fma_f32 v30, v30, v28, v28
	v_mul_f32_e32 v27, 0x3fb8aa3b, v27
	v_add_f32_e32 v29, v29, v29
	v_mul_f32_e32 v30, 0x3f4c422a, v30
	v_exp_f32_e32 v27, v27
	v_and_b32_e32 v23, 0xffff0000, v23
	v_mul_f32_e32 v29, 0x3fb8aa3b, v29
	v_add_f32_e32 v30, v30, v30
	v_exp_f32_e32 v29, v29
	v_mul_f32_e32 v30, 0x3fb8aa3b, v30
	v_mul_f32_e32 v36, 0x3d372713, v23
	v_exp_f32_e32 v30, v30
	v_mul_f32_e32 v36, v36, v23
	v_fma_f32 v36, v36, v23, v23
	v_add_f32_e32 v27, 1.0, v27
	v_mul_f32_e32 v36, 0x3f4c422a, v36
	v_rcp_f32_e32 v27, v27
	v_add_f32_e32 v29, 1.0, v29
	v_add_f32_e32 v36, v36, v36
	v_rcp_f32_e32 v29, v29
	v_rcp_f32_e32 v20, v20
	v_add_f32_e32 v30, 1.0, v30
	v_mul_f32_e32 v36, 0x3fb8aa3b, v36
	v_rcp_f32_e32 v30, v30
	v_exp_f32_e32 v36, v36
	v_fma_f32 v27, v27, -2.0, 1.0
	v_mul_f32_e32 v24, 0.5, v24
	v_add_f32_e32 v27, 1.0, v27
	v_fma_f32 v29, v29, -2.0, 1.0
	v_fma_f32 v20, v20, -2.0, 1.0
	v_fma_f32 v31, v24, v27, 0
	v_add_f32_e32 v29, 1.0, v29
	v_add_f32_e32 v37, 1.0, v20
	v_fma_f32 v20, v30, -2.0, 1.0
	v_add_f32_e32 v30, 1.0, v36
	v_fmac_f32_e32 v31, v32, v29
	v_mul_f32_e32 v25, 0.5, v25
	v_rcp_f32_e32 v30, v30
	v_fmac_f32_e32 v31, v25, v33
	v_mul_f32_e32 v21, 0.5, v21
	v_fmac_f32_e32 v31, v21, v34
	v_mul_f32_e32 v26, 0.5, v26
	v_fmac_f32_e32 v31, v26, v35
	v_mul_f32_e32 v22, 0.5, v22
	v_fmac_f32_e32 v31, v22, v37
	v_mul_f32_e32 v28, 0.5, v28
	v_add_f32_e32 v36, 1.0, v20
	v_fma_f32 v20, v30, -2.0, 1.0
	v_fmac_f32_e32 v31, v28, v36
	v_mul_f32_e32 v23, 0.5, v23
	v_add_f32_e32 v30, 1.0, v20
	v_fmac_f32_e32 v31, v23, v30
	s_nop 1
	v_add_f32_dpp v20, v31, v31 quad_perm:[1,0,3,2] row_mask:0xf bank_mask:0xf
	s_nop 1
	v_add_f32_dpp v20, v20, v20 quad_perm:[2,3,0,1] row_mask:0xf bank_mask:0xf
	s_nop 1
	v_add_f32_dpp v20, v20, v20 row_half_mirror row_mask:0xf bank_mask:0xf
	s_nop 1
	v_add_f32_dpp v20, v20, v20 row_mirror row_mask:0xf bank_mask:0xf
	s_nop 1
	v_add_f32_dpp v20, v20, v20 row_bcast:15 row_mask:0xa bank_mask:0xf
	s_nop 1
	v_add_f32_dpp v20, v20, v20 row_bcast:31 row_mask:0xc bank_mask:0xf
	s_nop 1
	v_readlane_b32 s58, v20, 63
	s_nop 1
	v_mov_b32_e32 v20, s58
	v_mul_f32_e32 v20, 0x3b000000, v20
	v_fma_f32 v24, v24, v27, -v20
	v_fma_f32 v27, v32, v29, -v20
	v_mul_f32_e32 v27, v27, v27
	v_fmac_f32_e32 v27, v24, v24
	v_fma_f32 v24, v25, v33, -v20
	v_fmac_f32_e32 v27, v24, v24
	v_fma_f32 v21, v21, v34, -v20
	v_fmac_f32_e32 v27, v21, v21
	v_fma_f32 v21, v26, v35, -v20
	v_fmac_f32_e32 v27, v21, v21
	v_fma_f32 v21, v22, v37, -v20
	v_fmac_f32_e32 v27, v21, v21
	v_fma_f32 v21, v28, v36, -v20
	v_fmac_f32_e32 v27, v21, v21
	v_fma_f32 v21, v23, v30, -v20
	v_fmac_f32_e32 v27, v21, v21
	s_nop 1
	v_add_f32_dpp v21, v27, v27 quad_perm:[1,0,3,2] row_mask:0xf bank_mask:0xf
	s_nop 1
	v_add_f32_dpp v21, v21, v21 quad_perm:[2,3,0,1] row_mask:0xf bank_mask:0xf
	s_nop 1
	v_add_f32_dpp v21, v21, v21 row_half_mirror row_mask:0xf bank_mask:0xf
	s_nop 1
	v_add_f32_dpp v21, v21, v21 row_mirror row_mask:0xf bank_mask:0xf
	s_nop 1
	v_add_f32_dpp v21, v21, v21 row_bcast:15 row_mask:0xa bank_mask:0xf
	s_nop 1
	v_add_f32_dpp v21, v21, v21 row_bcast:31 row_mask:0xc bank_mask:0xf
	s_nop 1
	v_readlane_b32 s58, v21, 63
	s_nop 1
	v_mov_b32_e32 v21, s58
	s_and_saveexec_b64 s[24:25], s[6:7]
	s_cbranch_execz .LBB0_149
; __device__ __forceinline__ void unpack8(const u32x4 w, float* f) { f[0] = bflo(w.x); f[1] = bfhi(w.x); f[2] = bflo(w.y); f[3] = bfhi(w.y); f[4] = bflo(w.z); f[5] = bfhi(w.z); f[6] = bflo(w.w); f[7] = bfhi(w.w); }
; __device__ __forceinline__ void gmlp_fast(KArgs ap, int l, LAS unsigned char* lds, const Ctx cx) {
;     ...
;         for (int j = 0; j < 8; ++j) { const int s = wave * 16 + i0 + j;
;             float v[8]; unpack8(raw[j], v);
;             float sm = 0.f;
; #pragma unroll
;             for (int e = 0; e < 8; ++e) { v[e] = gelu_tanh(v[e]); sm += v[e]; }
;             const float mean = wave_sum(sm) * (1.0f / 512.f);
;             float s2 = 0.f;
; #pragma unroll
;             for (int e = 0; e < 8; ++e) { const float d = v[e] - mean; s2 += d * d; }
;             const float rstd = 1.0f / sqrtf(wave_sum(s2) * (1.0f / 512.f) + EPS);
;             if (lane == 0) { ST[2 * s] = mean; ST[2 * s + 1] = rstd; } }
	v_fmamk_f32 v21, v21, 0x3b000000, v194
	s_mov_b32 s0, 0xf800000
	v_mul_f32_e32 v22, 0x4f800000, v21
	v_cmp_gt_f32_e32 vcc, s0, v21
	s_nop 1
	v_cndmask_b32_e32 v21, v21, v22, vcc
	v_sqrt_f32_e32 v22, v21
	s_nop 0
	v_add_u32_e32 v23, -1, v22
	v_fma_f32 v25, -v23, v22, v21
	v_add_u32_e32 v24, 1, v22
	v_cmp_ge_f32_e64 s[0:1], 0, v25
	s_nop 1
	v_cndmask_b32_e64 v23, v22, v23, s[0:1]
	v_fma_f32 v22, -v24, v22, v21
	v_cmp_lt_f32_e64 s[0:1], 0, v22
	s_nop 1
	v_cndmask_b32_e64 v22, v23, v24, s[0:1]
	v_mul_f32_e32 v23, 0x37800000, v22
	v_cndmask_b32_e32 v22, v22, v23, vcc
	v_cmp_class_f32_e32 vcc, v21, v195
	s_nop 1
	v_cndmask_b32_e32 v21, v22, v21, vcc
	v_div_scale_f32 v22, s[0:1], v21, v21, 1.0
	v_rcp_f32_e32 v23, v22
	s_lshl_b32 s0, s56, 3
	s_add_i32 s0, s0, 0
	s_add_i32 s0, s0, 0x11010
	v_fma_f32 v24, -v22, v23, 1.0
	v_fmac_f32_e32 v23, v24, v23
	v_div_scale_f32 v24, vcc, 1.0, v21, 1.0
	v_mul_f32_e32 v25, v24, v23
	v_fma_f32 v26, -v22, v25, v24
	v_fmac_f32_e32 v25, v26, v23
	v_fma_f32 v22, -v22, v25, v24
	v_div_fmas_f32 v22, v22, v23, v25
	v_div_fixup_f32 v21, v22, v21, 1.0
	v_mov_b32_e32 v22, s0
	ds_write_b64 v22, v[20:21]
.LBB0_149:
	s_or_b64 exec, exec, s[24:25]
	s_waitcnt vmcnt(4)
	v_lshlrev_b32_e32 v21, 16, v17
	v_mul_f32_e32 v26, 0x3d372713, v21
	v_mul_f32_e32 v26, v26, v21
	v_fma_f32 v26, v26, v21, v21
	v_mul_f32_e32 v26, 0x3f4c422a, v26
	v_add_f32_e32 v26, v26, v26
	v_mul_f32_e32 v26, 0x3fb8aa3b, v26
	v_exp_f32_e32 v26, v26
	v_lshlrev_b32_e32 v20, 16, v16
	v_and_b32_e32 v16, 0xffff0000, v16
	v_mul_f32_e32 v25, 0x3d372713, v16
	v_and_b32_e32 v17, 0xffff0000, v17
	v_mul_f32_e32 v25, v25, v16
	v_fma_f32 v25, v25, v16, v16
	v_mul_f32_e32 v28, 0.5, v16
	v_add_f32_e32 v16, 1.0, v26
	v_mul_f32_e32 v26, 0x3d372713, v17
	v_mul_f32_e32 v26, v26, v17
	v_fma_f32 v26, v26, v17, v17
	v_mul_f32_e32 v26, 0x3f4c422a, v26
	v_add_f32_e32 v26, v26, v26
	v_mul_f32_e32 v26, 0x3fb8aa3b, v26
	v_exp_f32_e32 v26, v26
	v_rcp_f32_e32 v16, v16
	s_waitcnt lgkmcnt(0)
	v_lshlrev_b32_e32 v22, 16, v18
	v_and_b32_e32 v18, 0xffff0000, v18
	v_add_f32_e32 v26, 1.0, v26
	v_rcp_f32_e32 v26, v26
	v_fma_f32 v16, v16, -2.0, 1.0
	v_add_f32_e32 v29, 1.0, v16
	v_mul_f32_e32 v23, 0x3d372713, v20
	v_fma_f32 v16, v26, -2.0, 1.0
	v_mul_f32_e32 v26, 0x3d372713, v22
	v_mul_f32_e32 v26, v26, v22
	v_fma_f32 v26, v26, v22, v22
	v_mul_f32_e32 v26, 0x3f4c422a, v26
	v_add_f32_e32 v26, v26, v26
	v_mul_f32_e32 v26, 0x3fb8aa3b, v26
	v_exp_f32_e32 v26, v26
	v_add_f32_e32 v30, 1.0, v16
	v_mul_f32_e32 v23, v23, v20
	v_lshlrev_b32_e32 v24, 16, v19
	v_add_f32_e32 v16, 1.0, v26
	v_mul_f32_e32 v26, 0x3d372713, v18
	v_mul_f32_e32 v26, v26, v18
	v_fma_f32 v26, v26, v18, v18
	v_mul_f32_e32 v26, 0x3f4c422a, v26
	v_add_f32_e32 v26, v26, v26
	v_rcp_f32_e32 v16, v16
	v_mul_f32_e32 v26, 0x3fb8aa3b, v26
	v_exp_f32_e32 v26, v26
	v_fma_f32 v23, v23, v20, v20
	v_fma_f32 v16, v16, -2.0, 1.0
	v_add_f32_e32 v31, 1.0, v16
	v_add_f32_e32 v16, 1.0, v26
	v_mul_f32_e32 v26, 0x3d372713, v24
	v_mul_f32_e32 v23, 0x3f4c422a, v23
	v_mul_f32_e32 v26, v26, v24
	v_add_f32_e32 v23, v23, v23
	v_mul_f32_e32 v25, 0x3f4c422a, v25
	v_fma_f32 v26, v26, v24, v24
	v_mul_f32_e32 v23, 0x3fb8aa3b, v23
	v_add_f32_e32 v25, v25, v25
	v_mul_f32_e32 v26, 0x3f4c422a, v26
	v_exp_f32_e32 v23, v23
	v_and_b32_e32 v19, 0xffff0000, v19
	v_mul_f32_e32 v25, 0x3fb8aa3b, v25
	v_add_f32_e32 v26, v26, v26
	v_exp_f32_e32 v25, v25
	v_mul_f32_e32 v26, 0x3fb8aa3b, v26
	v_mul_f32_e32 v32, 0x3d372713, v19
	v_exp_f32_e32 v26, v26
	v_mul_f32_e32 v32, v32, v19
	v_fma_f32 v32, v32, v19, v19
	v_add_f32_e32 v23, 1.0, v23
	v_mul_f32_e32 v32, 0x3f4c422a, v32
	v_rcp_f32_e32 v23, v23
	v_add_f32_e32 v25, 1.0, v25
	v_add_f32_e32 v32, v32, v32
	v_rcp_f32_e32 v25, v25
	v_rcp_f32_e32 v16, v16
	v_add_f32_e32 v26, 1.0, v26
	v_mul_f32_e32 v32, 0x3fb8aa3b, v32
	v_rcp_f32_e32 v26, v26
	v_exp_f32_e32 v32, v32
	v_fma_f32 v23, v23, -2.0, 1.0
	v_mul_f32_e32 v20, 0.5, v20
	v_add_f32_e32 v23, 1.0, v23
	v_fma_f32 v25, v25, -2.0, 1.0
	v_fma_f32 v16, v16, -2.0, 1.0
	v_fma_f32 v27, v20, v23, 0
	v_add_f32_e32 v25, 1.0, v25
	v_add_f32_e32 v33, 1.0, v16
	v_fma_f32 v16, v26, -2.0, 1.0
	v_add_f32_e32 v26, 1.0, v32
	v_fmac_f32_e32 v27, v28, v25
	v_mul_f32_e32 v21, 0.5, v21
	v_rcp_f32_e32 v26, v26
	v_fmac_f32_e32 v27, v21, v29
	v_mul_f32_e32 v17, 0.5, v17
	v_fmac_f32_e32 v27, v17, v30
	v_mul_f32_e32 v22, 0.5, v22
	v_fmac_f32_e32 v27, v22, v31
	v_mul_f32_e32 v18, 0.5, v18
	v_fmac_f32_e32 v27, v18, v33
	v_mul_f32_e32 v24, 0.5, v24
	v_add_f32_e32 v32, 1.0, v16
	v_fma_f32 v16, v26, -2.0, 1.0
	v_fmac_f32_e32 v27, v24, v32
	v_mul_f32_e32 v19, 0.5, v19
	v_add_f32_e32 v26, 1.0, v16
	v_fmac_f32_e32 v27, v19, v26
	s_nop 1
	v_add_f32_dpp v16, v27, v27 quad_perm:[1,0,3,2] row_mask:0xf bank_mask:0xf
	s_nop 1
	v_add_f32_dpp v16, v16, v16 quad_perm:[2,3,0,1] row_mask:0xf bank_mask:0xf
	s_nop 1
	v_add_f32_dpp v16, v16, v16 row_half_mirror row_mask:0xf bank_mask:0xf
	s_nop 1
	v_add_f32_dpp v16, v16, v16 row_mirror row_mask:0xf bank_mask:0xf
	s_nop 1
	v_add_f32_dpp v16, v16, v16 row_bcast:15 row_mask:0xa bank_mask:0xf
	s_nop 1
	v_add_f32_dpp v16, v16, v16 row_bcast:31 row_mask:0xc bank_mask:0xf
	s_nop 1
	v_readlane_b32 s58, v16, 63
	s_nop 1
	v_mov_b32_e32 v16, s58
	v_mul_f32_e32 v16, 0x3b000000, v16
	v_fma_f32 v20, v20, v23, -v16
	v_fma_f32 v23, v28, v25, -v16
	v_mul_f32_e32 v23, v23, v23
	v_fmac_f32_e32 v23, v20, v20
	v_fma_f32 v20, v21, v29, -v16
	v_fmac_f32_e32 v23, v20, v20
	v_fma_f32 v17, v17, v30, -v16
	v_fmac_f32_e32 v23, v17, v17
	v_fma_f32 v17, v22, v31, -v16
	v_fmac_f32_e32 v23, v17, v17
	v_fma_f32 v17, v18, v33, -v16
	v_fmac_f32_e32 v23, v17, v17
	v_fma_f32 v17, v24, v32, -v16
	v_fmac_f32_e32 v23, v17, v17
	v_fma_f32 v17, v19, v26, -v16
	v_fmac_f32_e32 v23, v17, v17
	s_nop 1
	v_add_f32_dpp v17, v23, v23 quad_perm:[1,0,3,2] row_mask:0xf bank_mask:0xf
	s_nop 1
	v_add_f32_dpp v17, v17, v17 quad_perm:[2,3,0,1] row_mask:0xf bank_mask:0xf
	s_nop 1
	v_add_f32_dpp v17, v17, v17 row_half_mirror row_mask:0xf bank_mask:0xf
	s_nop 1
	v_add_f32_dpp v17, v17, v17 row_mirror row_mask:0xf bank_mask:0xf
	s_nop 1
	v_add_f32_dpp v17, v17, v17 row_bcast:15 row_mask:0xa bank_mask:0xf
	s_nop 1
	v_add_f32_dpp v17, v17, v17 row_bcast:31 row_mask:0xc bank_mask:0xf
	s_nop 1
	v_readlane_b32 s58, v17, 63
	s_nop 1
	v_mov_b32_e32 v17, s58
	s_and_saveexec_b64 s[24:25], s[6:7]
	s_cbranch_execz .LBB0_151
; __device__ __forceinline__ void unpack8(const u32x4 w, float* f) { f[0] = bflo(w.x); f[1] = bfhi(w.x); f[2] = bflo(w.y); f[3] = bfhi(w.y); f[4] = bflo(w.z); f[5] = bfhi(w.z); f[6] = bflo(w.w); f[7] = bfhi(w.w); }
; __device__ __forceinline__ void gmlp_fast(KArgs ap, int l, LAS unsigned char* lds, const Ctx cx) {
;     ...
;         for (int j = 0; j < 8; ++j) { const int s = wave * 16 + i0 + j;
;             float v[8]; unpack8(raw[j], v);
;             float sm = 0.f;
; #pragma unroll
;             for (int e = 0; e < 8; ++e) { v[e] = gelu_tanh(v[e]); sm += v[e]; }
;             const float mean = wave_sum(sm) * (1.0f / 512.f);
;             float s2 = 0.f;
; #pragma unroll
;             for (int e = 0; e < 8; ++e) { const float d = v[e] - mean; s2 += d * d; }
;             const float rstd = 1.0f / sqrtf(wave_sum(s2) * (1.0f / 512.f) + EPS);
;             if (lane == 0) { ST[2 * s] = mean; ST[2 * s + 1] = rstd; } }
	v_fmamk_f32 v17, v17, 0x3b000000, v194
	s_mov_b32 s0, 0xf800000
	v_mul_f32_e32 v18, 0x4f800000, v17
	v_cmp_gt_f32_e32 vcc, s0, v17
	s_nop 1
	v_cndmask_b32_e32 v17, v17, v18, vcc
	v_sqrt_f32_e32 v18, v17
	s_nop 0
	v_add_u32_e32 v19, -1, v18
	v_fma_f32 v21, -v19, v18, v17
	v_add_u32_e32 v20, 1, v18
	v_cmp_ge_f32_e64 s[0:1], 0, v21
	s_nop 1
	v_cndmask_b32_e64 v19, v18, v19, s[0:1]
	v_fma_f32 v18, -v20, v18, v17
	v_cmp_lt_f32_e64 s[0:1], 0, v18
	s_nop 1
	v_cndmask_b32_e64 v18, v19, v20, s[0:1]
	v_mul_f32_e32 v19, 0x37800000, v18
	v_cndmask_b32_e32 v18, v18, v19, vcc
	v_cmp_class_f32_e32 vcc, v17, v195
	s_nop 1
	v_cndmask_b32_e32 v17, v18, v17, vcc
	v_div_scale_f32 v18, s[0:1], v17, v17, 1.0
	v_rcp_f32_e32 v19, v18
	s_lshl_b32 s0, s56, 3
	s_add_i32 s0, s0, 0
	s_add_i32 s0, s0, 0x11018
	v_fma_f32 v20, -v18, v19, 1.0
	v_fmac_f32_e32 v19, v20, v19
	v_div_scale_f32 v20, vcc, 1.0, v17, 1.0
	v_mul_f32_e32 v21, v20, v19
	v_fma_f32 v22, -v18, v21, v20
	v_fmac_f32_e32 v21, v22, v19
	v_fma_f32 v18, -v18, v21, v20
	v_div_fmas_f32 v18, v18, v19, v21
	v_div_fixup_f32 v17, v18, v17, 1.0
	v_mov_b32_e32 v18, s0
	ds_write_b64 v18, v[16:17]
.LBB0_151:
	s_or_b64 exec, exec, s[24:25]
	s_waitcnt vmcnt(3)
	v_lshlrev_b32_e32 v17, 16, v13
	v_mul_f32_e32 v22, 0x3d372713, v17
	v_mul_f32_e32 v22, v22, v17
	v_fma_f32 v22, v22, v17, v17
	v_mul_f32_e32 v22, 0x3f4c422a, v22
	v_add_f32_e32 v22, v22, v22
	v_mul_f32_e32 v22, 0x3fb8aa3b, v22
	v_exp_f32_e32 v22, v22
	v_lshlrev_b32_e32 v16, 16, v12
	v_and_b32_e32 v12, 0xffff0000, v12
	v_mul_f32_e32 v21, 0x3d372713, v12
	v_and_b32_e32 v13, 0xffff0000, v13
	v_mul_f32_e32 v21, v21, v12
	v_fma_f32 v21, v21, v12, v12
	v_mul_f32_e32 v24, 0.5, v12
	v_add_f32_e32 v12, 1.0, v22
	v_mul_f32_e32 v22, 0x3d372713, v13
	v_mul_f32_e32 v22, v22, v13
	v_fma_f32 v22, v22, v13, v13
	v_mul_f32_e32 v22, 0x3f4c422a, v22
	v_add_f32_e32 v22, v22, v22
	v_mul_f32_e32 v22, 0x3fb8aa3b, v22
	v_exp_f32_e32 v22, v22
	v_rcp_f32_e32 v12, v12
	s_waitcnt lgkmcnt(0)
	v_lshlrev_b32_e32 v18, 16, v14
	v_and_b32_e32 v14, 0xffff0000, v14
	v_add_f32_e32 v22, 1.0, v22
	v_rcp_f32_e32 v22, v22
	v_fma_f32 v12, v12, -2.0, 1.0
	v_add_f32_e32 v25, 1.0, v12
	v_mul_f32_e32 v19, 0x3d372713, v16
	v_fma_f32 v12, v22, -2.0, 1.0
	v_mul_f32_e32 v22, 0x3d372713, v18
	v_mul_f32_e32 v22, v22, v18
	v_fma_f32 v22, v22, v18, v18
	v_mul_f32_e32 v22, 0x3f4c422a, v22
	v_add_f32_e32 v22, v22, v22
	v_mul_f32_e32 v22, 0x3fb8aa3b, v22
	v_exp_f32_e32 v22, v22
	v_add_f32_e32 v26, 1.0, v12
	v_mul_f32_e32 v19, v19, v16
	v_lshlrev_b32_e32 v20, 16, v15
	v_add_f32_e32 v12, 1.0, v22
	v_mul_f32_e32 v22, 0x3d372713, v14
	v_mul_f32_e32 v22, v22, v14
	v_fma_f32 v22, v22, v14, v14
	v_mul_f32_e32 v22, 0x3f4c422a, v22
	v_add_f32_e32 v22, v22, v22
	v_rcp_f32_e32 v12, v12
	v_mul_f32_e32 v22, 0x3fb8aa3b, v22
	v_exp_f32_e32 v22, v22
	v_fma_f32 v19, v19, v16, v16
	v_fma_f32 v12, v12, -2.0, 1.0
	v_add_f32_e32 v27, 1.0, v12
	v_add_f32_e32 v12, 1.0, v22
	v_mul_f32_e32 v22, 0x3d372713, v20
	v_mul_f32_e32 v19, 0x3f4c422a, v19
	v_mul_f32_e32 v22, v22, v20
	v_add_f32_e32 v19, v19, v19
	v_mul_f32_e32 v21, 0x3f4c422a, v21
	v_fma_f32 v22, v22, v20, v20
	v_mul_f32_e32 v19, 0x3fb8aa3b, v19
	v_add_f32_e32 v21, v21, v21
	v_mul_f32_e32 v22, 0x3f4c422a, v22
	v_exp_f32_e32 v19, v19
	v_and_b32_e32 v15, 0xffff0000, v15
	v_mul_f32_e32 v21, 0x3fb8aa3b, v21
	v_add_f32_e32 v22, v22, v22
	v_exp_f32_e32 v21, v21
	v_mul_f32_e32 v22, 0x3fb8aa3b, v22
	v_mul_f32_e32 v28, 0x3d372713, v15
	v_exp_f32_e32 v22, v22
	v_mul_f32_e32 v28, v28, v15
	v_fma_f32 v28, v28, v15, v15
	v_add_f32_e32 v19, 1.0, v19
	v_mul_f32_e32 v28, 0x3f4c422a, v28
	v_rcp_f32_e32 v19, v19
	v_add_f32_e32 v21, 1.0, v21
	v_add_f32_e32 v28, v28, v28
	v_rcp_f32_e32 v21, v21
	v_rcp_f32_e32 v12, v12
	v_add_f32_e32 v22, 1.0, v22
	v_mul_f32_e32 v28, 0x3fb8aa3b, v28
	v_rcp_f32_e32 v22, v22
	v_exp_f32_e32 v28, v28
	v_fma_f32 v19, v19, -2.0, 1.0
	v_mul_f32_e32 v16, 0.5, v16
	v_add_f32_e32 v19, 1.0, v19
	v_fma_f32 v21, v21, -2.0, 1.0
	v_fma_f32 v12, v12, -2.0, 1.0
	v_fma_f32 v23, v16, v19, 0
	v_add_f32_e32 v21, 1.0, v21
	v_add_f32_e32 v29, 1.0, v12
	v_fma_f32 v12, v22, -2.0, 1.0
	v_add_f32_e32 v22, 1.0, v28
	v_fmac_f32_e32 v23, v24, v21
	v_mul_f32_e32 v17, 0.5, v17
	v_rcp_f32_e32 v22, v22
	v_fmac_f32_e32 v23, v17, v25
	v_mul_f32_e32 v13, 0.5, v13
	v_fmac_f32_e32 v23, v13, v26
	v_mul_f32_e32 v18, 0.5, v18
	v_fmac_f32_e32 v23, v18, v27
	v_mul_f32_e32 v14, 0.5, v14
	v_fmac_f32_e32 v23, v14, v29
	v_mul_f32_e32 v20, 0.5, v20
	v_add_f32_e32 v28, 1.0, v12
	v_fma_f32 v12, v22, -2.0, 1.0
	v_fmac_f32_e32 v23, v20, v28
	v_mul_f32_e32 v15, 0.5, v15
	v_add_f32_e32 v22, 1.0, v12
	v_fmac_f32_e32 v23, v15, v22
	s_nop 1
	v_add_f32_dpp v12, v23, v23 quad_perm:[1,0,3,2] row_mask:0xf bank_mask:0xf
	s_nop 1
	v_add_f32_dpp v12, v12, v12 quad_perm:[2,3,0,1] row_mask:0xf bank_mask:0xf
	s_nop 1
	v_add_f32_dpp v12, v12, v12 row_half_mirror row_mask:0xf bank_mask:0xf
	s_nop 1
	v_add_f32_dpp v12, v12, v12 row_mirror row_mask:0xf bank_mask:0xf
	s_nop 1
	v_add_f32_dpp v12, v12, v12 row_bcast:15 row_mask:0xa bank_mask:0xf
	s_nop 1
	v_add_f32_dpp v12, v12, v12 row_bcast:31 row_mask:0xc bank_mask:0xf
	s_nop 1
	v_readlane_b32 s58, v12, 63
	s_nop 1
	v_mov_b32_e32 v12, s58
	v_mul_f32_e32 v12, 0x3b000000, v12
	v_fma_f32 v16, v16, v19, -v12
	v_fma_f32 v19, v24, v21, -v12
	v_mul_f32_e32 v19, v19, v19
	v_fmac_f32_e32 v19, v16, v16
	v_fma_f32 v16, v17, v25, -v12
	v_fmac_f32_e32 v19, v16, v16
	v_fma_f32 v13, v13, v26, -v12
	v_fmac_f32_e32 v19, v13, v13
	v_fma_f32 v13, v18, v27, -v12
	v_fmac_f32_e32 v19, v13, v13
	v_fma_f32 v13, v14, v29, -v12
	v_fmac_f32_e32 v19, v13, v13
	v_fma_f32 v13, v20, v28, -v12
	v_fmac_f32_e32 v19, v13, v13
	v_fma_f32 v13, v15, v22, -v12
	v_fmac_f32_e32 v19, v13, v13
	s_nop 1
	v_add_f32_dpp v13, v19, v19 quad_perm:[1,0,3,2] row_mask:0xf bank_mask:0xf
	s_nop 1
	v_add_f32_dpp v13, v13, v13 quad_perm:[2,3,0,1] row_mask:0xf bank_mask:0xf
	s_nop 1
	v_add_f32_dpp v13, v13, v13 row_half_mirror row_mask:0xf bank_mask:0xf
	s_nop 1
	v_add_f32_dpp v13, v13, v13 row_mirror row_mask:0xf bank_mask:0xf
	s_nop 1
	v_add_f32_dpp v13, v13, v13 row_bcast:15 row_mask:0xa bank_mask:0xf
	s_nop 1
	v_add_f32_dpp v13, v13, v13 row_bcast:31 row_mask:0xc bank_mask:0xf
	s_nop 1
	v_readlane_b32 s58, v13, 63
	s_nop 1
	v_mov_b32_e32 v13, s58
	s_and_saveexec_b64 s[24:25], s[6:7]
	s_cbranch_execz .LBB0_153
; __device__ __forceinline__ void unpack8(const u32x4 w, float* f) { f[0] = bflo(w.x); f[1] = bfhi(w.x); f[2] = bflo(w.y); f[3] = bfhi(w.y); f[4] = bflo(w.z); f[5] = bfhi(w.z); f[6] = bflo(w.w); f[7] = bfhi(w.w); }
; __device__ __forceinline__ void gmlp_fast(KArgs ap, int l, LAS unsigned char* lds, const Ctx cx) {
;     ...
;         for (int j = 0; j < 8; ++j) { const int s = wave * 16 + i0 + j;
;             float v[8]; unpack8(raw[j], v);
;             float sm = 0.f;
; #pragma unroll
;             for (int e = 0; e < 8; ++e) { v[e] = gelu_tanh(v[e]); sm += v[e]; }
;             const float mean = wave_sum(sm) * (1.0f / 512.f);
;             float s2 = 0.f;
; #pragma unroll
;             for (int e = 0; e < 8; ++e) { const float d = v[e] - mean; s2 += d * d; }
;             const float rstd = 1.0f / sqrtf(wave_sum(s2) * (1.0f / 512.f) + EPS);
;             if (lane == 0) { ST[2 * s] = mean; ST[2 * s + 1] = rstd; } }
	v_fmamk_f32 v13, v13, 0x3b000000, v194
	s_mov_b32 s0, 0xf800000
	v_mul_f32_e32 v14, 0x4f800000, v13
	v_cmp_gt_f32_e32 vcc, s0, v13
	s_nop 1
	v_cndmask_b32_e32 v13, v13, v14, vcc
	v_sqrt_f32_e32 v14, v13
	s_nop 0
	v_add_u32_e32 v15, -1, v14
	v_fma_f32 v17, -v15, v14, v13
	v_add_u32_e32 v16, 1, v14
	v_cmp_ge_f32_e64 s[0:1], 0, v17
	s_nop 1
	v_cndmask_b32_e64 v15, v14, v15, s[0:1]
	v_fma_f32 v14, -v16, v14, v13
	v_cmp_lt_f32_e64 s[0:1], 0, v14
	s_nop 1
	v_cndmask_b32_e64 v14, v15, v16, s[0:1]
	v_mul_f32_e32 v15, 0x37800000, v14
	v_cndmask_b32_e32 v14, v14, v15, vcc
	v_cmp_class_f32_e32 vcc, v13, v195
	s_nop 1
	v_cndmask_b32_e32 v13, v14, v13, vcc
	v_div_scale_f32 v14, s[0:1], v13, v13, 1.0
	v_rcp_f32_e32 v15, v14
	s_lshl_b32 s0, s56, 3
	s_add_i32 s0, s0, 0
	s_add_i32 s0, s0, 0x11020
	v_fma_f32 v16, -v14, v15, 1.0
	v_fmac_f32_e32 v15, v16, v15
	v_div_scale_f32 v16, vcc, 1.0, v13, 1.0
	v_mul_f32_e32 v17, v16, v15
	v_fma_f32 v18, -v14, v17, v16
	v_fmac_f32_e32 v17, v18, v15
	v_fma_f32 v14, -v14, v17, v16
	v_div_fmas_f32 v14, v14, v15, v17
	v_div_fixup_f32 v13, v14, v13, 1.0
	v_mov_b32_e32 v14, s0
	ds_write_b64 v14, v[12:13]
.LBB0_153:
	s_or_b64 exec, exec, s[24:25]
	s_waitcnt vmcnt(2)
	v_lshlrev_b32_e32 v13, 16, v5
	v_mul_f32_e32 v18, 0x3d372713, v13
	v_mul_f32_e32 v18, v18, v13
	v_fma_f32 v18, v18, v13, v13
	v_mul_f32_e32 v18, 0x3f4c422a, v18
	v_add_f32_e32 v18, v18, v18
	v_mul_f32_e32 v18, 0x3fb8aa3b, v18
	v_exp_f32_e32 v18, v18
	v_lshlrev_b32_e32 v12, 16, v4
	v_and_b32_e32 v4, 0xffff0000, v4
	v_mul_f32_e32 v17, 0x3d372713, v4
	v_and_b32_e32 v5, 0xffff0000, v5
	v_mul_f32_e32 v17, v17, v4
	v_fma_f32 v17, v17, v4, v4
	v_mul_f32_e32 v20, 0.5, v4
	v_add_f32_e32 v4, 1.0, v18
	v_mul_f32_e32 v18, 0x3d372713, v5
	v_mul_f32_e32 v18, v18, v5
	v_fma_f32 v18, v18, v5, v5
	v_mul_f32_e32 v18, 0x3f4c422a, v18
	v_add_f32_e32 v18, v18, v18
	v_mul_f32_e32 v18, 0x3fb8aa3b, v18
	v_exp_f32_e32 v18, v18
	v_rcp_f32_e32 v4, v4
	s_waitcnt lgkmcnt(0)
	v_lshlrev_b32_e32 v14, 16, v6
	v_and_b32_e32 v6, 0xffff0000, v6
	v_add_f32_e32 v18, 1.0, v18
	v_rcp_f32_e32 v18, v18
	v_fma_f32 v4, v4, -2.0, 1.0
	v_add_f32_e32 v21, 1.0, v4
	v_mul_f32_e32 v15, 0x3d372713, v12
	v_fma_f32 v4, v18, -2.0, 1.0
	v_mul_f32_e32 v18, 0x3d372713, v14
	v_mul_f32_e32 v18, v18, v14
	v_fma_f32 v18, v18, v14, v14
	v_mul_f32_e32 v18, 0x3f4c422a, v18
	v_add_f32_e32 v18, v18, v18
	v_mul_f32_e32 v18, 0x3fb8aa3b, v18
	v_exp_f32_e32 v18, v18
	v_add_f32_e32 v22, 1.0, v4
	v_mul_f32_e32 v15, v15, v12
	v_lshlrev_b32_e32 v16, 16, v7
	v_add_f32_e32 v4, 1.0, v18
	v_mul_f32_e32 v18, 0x3d372713, v6
	v_mul_f32_e32 v18, v18, v6
	v_fma_f32 v18, v18, v6, v6
	v_mul_f32_e32 v18, 0x3f4c422a, v18
	v_add_f32_e32 v18, v18, v18
	v_rcp_f32_e32 v4, v4
	v_mul_f32_e32 v18, 0x3fb8aa3b, v18
	v_exp_f32_e32 v18, v18
	v_fma_f32 v15, v15, v12, v12
	v_fma_f32 v4, v4, -2.0, 1.0
	v_add_f32_e32 v23, 1.0, v4
	v_add_f32_e32 v4, 1.0, v18
	v_mul_f32_e32 v18, 0x3d372713, v16
	v_mul_f32_e32 v15, 0x3f4c422a, v15
	v_mul_f32_e32 v18, v18, v16
	v_add_f32_e32 v15, v15, v15
	v_mul_f32_e32 v17, 0x3f4c422a, v17
	v_fma_f32 v18, v18, v16, v16
	v_mul_f32_e32 v15, 0x3fb8aa3b, v15
	v_add_f32_e32 v17, v17, v17
	v_mul_f32_e32 v18, 0x3f4c422a, v18
	v_exp_f32_e32 v15, v15
	v_and_b32_e32 v7, 0xffff0000, v7
	v_mul_f32_e32 v17, 0x3fb8aa3b, v17
	v_add_f32_e32 v18, v18, v18
	v_exp_f32_e32 v17, v17
	v_mul_f32_e32 v18, 0x3fb8aa3b, v18
	v_mul_f32_e32 v24, 0x3d372713, v7
	v_exp_f32_e32 v18, v18
	v_mul_f32_e32 v24, v24, v7
	v_fma_f32 v24, v24, v7, v7
	v_add_f32_e32 v15, 1.0, v15
	v_mul_f32_e32 v24, 0x3f4c422a, v24
	v_rcp_f32_e32 v15, v15
	v_add_f32_e32 v17, 1.0, v17
	v_add_f32_e32 v24, v24, v24
	v_rcp_f32_e32 v17, v17
	v_rcp_f32_e32 v4, v4
	v_add_f32_e32 v18, 1.0, v18
	v_mul_f32_e32 v24, 0x3fb8aa3b, v24
	v_rcp_f32_e32 v18, v18
	v_exp_f32_e32 v24, v24
	v_fma_f32 v15, v15, -2.0, 1.0
	v_mul_f32_e32 v12, 0.5, v12
	v_add_f32_e32 v15, 1.0, v15
	v_fma_f32 v17, v17, -2.0, 1.0
	v_fma_f32 v4, v4, -2.0, 1.0
	v_fma_f32 v19, v12, v15, 0
	v_add_f32_e32 v17, 1.0, v17
	v_add_f32_e32 v25, 1.0, v4
	v_fma_f32 v4, v18, -2.0, 1.0
	v_add_f32_e32 v18, 1.0, v24
	v_fmac_f32_e32 v19, v20, v17
	v_mul_f32_e32 v13, 0.5, v13
	v_rcp_f32_e32 v18, v18
	v_fmac_f32_e32 v19, v13, v21
	v_mul_f32_e32 v5, 0.5, v5
	v_fmac_f32_e32 v19, v5, v22
	v_mul_f32_e32 v14, 0.5, v14
	v_fmac_f32_e32 v19, v14, v23
	v_mul_f32_e32 v6, 0.5, v6
	v_fmac_f32_e32 v19, v6, v25
	v_mul_f32_e32 v16, 0.5, v16
	v_add_f32_e32 v24, 1.0, v4
	v_fma_f32 v4, v18, -2.0, 1.0
	v_fmac_f32_e32 v19, v16, v24
	v_mul_f32_e32 v7, 0.5, v7
	v_add_f32_e32 v18, 1.0, v4
	v_fmac_f32_e32 v19, v7, v18
	s_nop 1
	v_add_f32_dpp v4, v19, v19 quad_perm:[1,0,3,2] row_mask:0xf bank_mask:0xf
	s_nop 1
	v_add_f32_dpp v4, v4, v4 quad_perm:[2,3,0,1] row_mask:0xf bank_mask:0xf
	s_nop 1
	v_add_f32_dpp v4, v4, v4 row_half_mirror row_mask:0xf bank_mask:0xf
	s_nop 1
	v_add_f32_dpp v4, v4, v4 row_mirror row_mask:0xf bank_mask:0xf
	s_nop 1
	v_add_f32_dpp v4, v4, v4 row_bcast:15 row_mask:0xa bank_mask:0xf
	s_nop 1
	v_add_f32_dpp v4, v4, v4 row_bcast:31 row_mask:0xc bank_mask:0xf
	s_nop 1
	v_readlane_b32 s58, v4, 63
	s_nop 1
	v_mov_b32_e32 v4, s58
	v_mul_f32_e32 v4, 0x3b000000, v4
	v_fma_f32 v12, v12, v15, -v4
	v_fma_f32 v15, v20, v17, -v4
	v_mul_f32_e32 v15, v15, v15
	v_fmac_f32_e32 v15, v12, v12
	v_fma_f32 v12, v13, v21, -v4
	v_fmac_f32_e32 v15, v12, v12
	v_fma_f32 v5, v5, v22, -v4
	v_fmac_f32_e32 v15, v5, v5
	v_fma_f32 v5, v14, v23, -v4
	v_fmac_f32_e32 v15, v5, v5
	v_fma_f32 v5, v6, v25, -v4
	v_fmac_f32_e32 v15, v5, v5
	v_fma_f32 v5, v16, v24, -v4
	v_fmac_f32_e32 v15, v5, v5
	v_fma_f32 v5, v7, v18, -v4
	v_fmac_f32_e32 v15, v5, v5
	s_nop 1
	v_add_f32_dpp v5, v15, v15 quad_perm:[1,0,3,2] row_mask:0xf bank_mask:0xf
	s_nop 1
	v_add_f32_dpp v5, v5, v5 quad_perm:[2,3,0,1] row_mask:0xf bank_mask:0xf
	s_nop 1
	v_add_f32_dpp v5, v5, v5 row_half_mirror row_mask:0xf bank_mask:0xf
	s_nop 1
	v_add_f32_dpp v5, v5, v5 row_mirror row_mask:0xf bank_mask:0xf
	s_nop 1
	v_add_f32_dpp v5, v5, v5 row_bcast:15 row_mask:0xa bank_mask:0xf
	s_nop 1
	v_add_f32_dpp v5, v5, v5 row_bcast:31 row_mask:0xc bank_mask:0xf
	s_nop 1
	v_readlane_b32 s58, v5, 63
	s_nop 1
	v_mov_b32_e32 v5, s58
	s_and_saveexec_b64 s[24:25], s[6:7]
	s_cbranch_execz .LBB0_155
; __device__ __forceinline__ void unpack8(const u32x4 w, float* f) { f[0] = bflo(w.x); f[1] = bfhi(w.x); f[2] = bflo(w.y); f[3] = bfhi(w.y); f[4] = bflo(w.z); f[5] = bfhi(w.z); f[6] = bflo(w.w); f[7] = bfhi(w.w); }
; __device__ __forceinline__ void gmlp_fast(KArgs ap, int l, LAS unsigned char* lds, const Ctx cx) {
;     ...
;         for (int j = 0; j < 8; ++j) { const int s = wave * 16 + i0 + j;
;             float v[8]; unpack8(raw[j], v);
;             float sm = 0.f;
; #pragma unroll
;             for (int e = 0; e < 8; ++e) { v[e] = gelu_tanh(v[e]); sm += v[e]; }
;             const float mean = wave_sum(sm) * (1.0f / 512.f);
;             float s2 = 0.f;
; #pragma unroll
;             for (int e = 0; e < 8; ++e) { const float d = v[e] - mean; s2 += d * d; }
;             const float rstd = 1.0f / sqrtf(wave_sum(s2) * (1.0f / 512.f) + EPS);
;             if (lane == 0) { ST[2 * s] = mean; ST[2 * s + 1] = rstd; } }
	v_fmamk_f32 v5, v5, 0x3b000000, v194
	s_mov_b32 s0, 0xf800000
	v_mul_f32_e32 v6, 0x4f800000, v5
	v_cmp_gt_f32_e32 vcc, s0, v5
	s_nop 1
	v_cndmask_b32_e32 v5, v5, v6, vcc
	v_sqrt_f32_e32 v6, v5
	s_nop 0
	v_add_u32_e32 v7, -1, v6
	v_fma_f32 v13, -v7, v6, v5
	v_add_u32_e32 v12, 1, v6
	v_cmp_ge_f32_e64 s[0:1], 0, v13
	s_nop 1
	v_cndmask_b32_e64 v7, v6, v7, s[0:1]
	v_fma_f32 v6, -v12, v6, v5
	v_cmp_lt_f32_e64 s[0:1], 0, v6
	s_nop 1
	v_cndmask_b32_e64 v6, v7, v12, s[0:1]
	v_mul_f32_e32 v7, 0x37800000, v6
	v_cndmask_b32_e32 v6, v6, v7, vcc
	v_cmp_class_f32_e32 vcc, v5, v195
	s_nop 1
	v_cndmask_b32_e32 v5, v6, v5, vcc
	v_div_scale_f32 v6, s[0:1], v5, v5, 1.0
	v_rcp_f32_e32 v7, v6
	s_lshl_b32 s0, s56, 3
	s_add_i32 s0, s0, 0
	s_add_i32 s0, s0, 0x11028
	v_fma_f32 v12, -v6, v7, 1.0
	v_fmac_f32_e32 v7, v12, v7
	v_div_scale_f32 v12, vcc, 1.0, v5, 1.0
	v_mul_f32_e32 v13, v12, v7
	v_fma_f32 v14, -v6, v13, v12
	v_fmac_f32_e32 v13, v14, v7
	v_fma_f32 v6, -v6, v13, v12
	v_div_fmas_f32 v6, v6, v7, v13
	v_div_fixup_f32 v5, v6, v5, 1.0
	v_mov_b32_e32 v6, s0
	ds_write_b64 v6, v[4:5]
.LBB0_155:
	s_or_b64 exec, exec, s[24:25]
	s_waitcnt vmcnt(1)
	v_and_b32_e32 v5, 0xffff0000, v8
	v_mul_f32_e32 v13, 0x3d372713, v5
	v_mul_f32_e32 v13, v13, v5
	v_fma_f32 v13, v13, v5, v5
	v_mul_f32_e32 v13, 0x3f4c422a, v13
	v_add_f32_e32 v13, v13, v13
	v_mul_f32_e32 v13, 0x3fb8aa3b, v13
	v_exp_f32_e32 v13, v13
	v_lshlrev_b32_e32 v4, 16, v8
	s_waitcnt lgkmcnt(0)
	v_lshlrev_b32_e32 v6, 16, v9
	v_and_b32_e32 v7, 0xffff0000, v9
	v_mul_f32_e32 v9, 0x3d372713, v4
	v_mul_f32_e32 v9, v9, v4
	v_fma_f32 v9, v9, v4, v4
	v_mul_f32_e32 v14, 0.5, v4
	v_add_f32_e32 v4, 1.0, v13
	v_mul_f32_e32 v13, 0x3d372713, v6
	v_mul_f32_e32 v13, v13, v6
	v_fma_f32 v13, v13, v6, v6
	v_mul_f32_e32 v13, 0x3f4c422a, v13
	v_add_f32_e32 v13, v13, v13
	v_mul_f32_e32 v13, 0x3fb8aa3b, v13
	v_mul_f32_e32 v16, 0x3d372713, v7
	v_exp_f32_e32 v13, v13
	v_mul_f32_e32 v16, v16, v7
	v_fma_f32 v16, v16, v7, v7
	v_mul_f32_e32 v16, 0x3f4c422a, v16
	v_add_f32_e32 v16, v16, v16
	v_rcp_f32_e32 v4, v4
	v_add_f32_e32 v13, 1.0, v13
	v_mul_f32_e32 v16, 0x3fb8aa3b, v16
	v_rcp_f32_e32 v13, v13
	v_exp_f32_e32 v16, v16
	v_fma_f32 v4, v4, -2.0, 1.0
	v_add_f32_e32 v17, 1.0, v4
	v_fma_f32 v4, v13, -2.0, 1.0
	v_add_f32_e32 v13, 1.0, v16
	v_rcp_f32_e32 v13, v13
	v_lshlrev_b32_e32 v8, 16, v10
	v_add_f32_e32 v16, 1.0, v4
	v_and_b32_e32 v10, 0xffff0000, v10
	v_fma_f32 v4, v13, -2.0, 1.0
	v_mul_f32_e32 v13, 0x3d372713, v8
	v_mul_f32_e32 v13, v13, v8
	v_fma_f32 v13, v13, v8, v8
	v_mul_f32_e32 v13, 0x3f4c422a, v13
	v_add_f32_e32 v13, v13, v13
	v_mul_f32_e32 v13, 0x3fb8aa3b, v13
	v_exp_f32_e32 v13, v13
	v_add_f32_e32 v18, 1.0, v4
	v_lshlrev_b32_e32 v12, 16, v11
	v_mul_f32_e32 v9, 0x3f4c422a, v9
	v_add_f32_e32 v4, 1.0, v13
	v_mul_f32_e32 v13, 0x3d372713, v10
	v_mul_f32_e32 v13, v13, v10
	v_fma_f32 v13, v13, v10, v10
	v_mul_f32_e32 v13, 0x3f4c422a, v13
	v_add_f32_e32 v13, v13, v13
	v_rcp_f32_e32 v4, v4
	v_mul_f32_e32 v13, 0x3fb8aa3b, v13
	v_exp_f32_e32 v13, v13
	v_add_f32_e32 v9, v9, v9
	v_fma_f32 v4, v4, -2.0, 1.0
	v_add_f32_e32 v19, 1.0, v4
	v_add_f32_e32 v4, 1.0, v13
	v_mul_f32_e32 v13, 0x3d372713, v12
	v_mul_f32_e32 v13, v13, v12
	v_fma_f32 v13, v13, v12, v12
	v_mul_f32_e32 v9, 0x3fb8aa3b, v9
	v_mul_f32_e32 v13, 0x3f4c422a, v13
	v_exp_f32_e32 v9, v9
	v_and_b32_e32 v11, 0xffff0000, v11
	v_add_f32_e32 v13, v13, v13
	v_mul_f32_e32 v13, 0x3fb8aa3b, v13
	v_mul_f32_e32 v20, 0x3d372713, v11
	v_exp_f32_e32 v13, v13
	v_mul_f32_e32 v20, v20, v11
	v_fma_f32 v20, v20, v11, v11
	v_add_f32_e32 v9, 1.0, v9
	v_mul_f32_e32 v20, 0x3f4c422a, v20
	v_rcp_f32_e32 v9, v9
	v_add_f32_e32 v20, v20, v20
	v_rcp_f32_e32 v4, v4
	v_add_f32_e32 v13, 1.0, v13
	v_mul_f32_e32 v20, 0x3fb8aa3b, v20
	v_rcp_f32_e32 v13, v13
	v_exp_f32_e32 v20, v20
	v_fma_f32 v9, v9, -2.0, 1.0
	v_add_f32_e32 v9, 1.0, v9
	v_fma_f32 v4, v4, -2.0, 1.0
	v_fma_f32 v15, v14, v9, 0
	v_mul_f32_e32 v5, 0.5, v5
	v_add_f32_e32 v21, 1.0, v4
	v_fma_f32 v4, v13, -2.0, 1.0
	v_add_f32_e32 v13, 1.0, v20
	v_fmac_f32_e32 v15, v5, v17
	v_mul_f32_e32 v6, 0.5, v6
	v_rcp_f32_e32 v13, v13
	v_fmac_f32_e32 v15, v6, v16
	v_mul_f32_e32 v7, 0.5, v7
	v_fmac_f32_e32 v15, v7, v18
	v_mul_f32_e32 v8, 0.5, v8
	v_fmac_f32_e32 v15, v8, v19
	v_mul_f32_e32 v10, 0.5, v10
	v_fmac_f32_e32 v15, v10, v21
	v_mul_f32_e32 v12, 0.5, v12
	v_add_f32_e32 v20, 1.0, v4
	v_fma_f32 v4, v13, -2.0, 1.0
	v_fmac_f32_e32 v15, v12, v20
	v_mul_f32_e32 v11, 0.5, v11
	v_add_f32_e32 v13, 1.0, v4
	v_fmac_f32_e32 v15, v11, v13
	s_nop 1
	v_add_f32_dpp v4, v15, v15 quad_perm:[1,0,3,2] row_mask:0xf bank_mask:0xf
	s_nop 1
	v_add_f32_dpp v4, v4, v4 quad_perm:[2,3,0,1] row_mask:0xf bank_mask:0xf
	s_nop 1
	v_add_f32_dpp v4, v4, v4 row_half_mirror row_mask:0xf bank_mask:0xf
	s_nop 1
	v_add_f32_dpp v4, v4, v4 row_mirror row_mask:0xf bank_mask:0xf
	s_nop 1
	v_add_f32_dpp v4, v4, v4 row_bcast:15 row_mask:0xa bank_mask:0xf
	s_nop 1
	v_add_f32_dpp v4, v4, v4 row_bcast:31 row_mask:0xc bank_mask:0xf
	s_nop 1
	v_readlane_b32 s58, v4, 63
	s_nop 1
	v_mov_b32_e32 v4, s58
	v_mul_f32_e32 v4, 0x3b000000, v4
	v_fma_f32 v5, v5, v17, -v4
	v_fma_f32 v9, v14, v9, -v4
	v_mul_f32_e32 v5, v5, v5
	v_fmac_f32_e32 v5, v9, v9
	v_fma_f32 v6, v6, v16, -v4
	v_fmac_f32_e32 v5, v6, v6
	v_fma_f32 v6, v7, v18, -v4
	v_fmac_f32_e32 v5, v6, v6
	v_fma_f32 v6, v8, v19, -v4
	v_fmac_f32_e32 v5, v6, v6
	v_fma_f32 v6, v10, v21, -v4
	v_fmac_f32_e32 v5, v6, v6
	v_fma_f32 v6, v12, v20, -v4
	v_fmac_f32_e32 v5, v6, v6
	v_fma_f32 v6, v11, v13, -v4
	v_fmac_f32_e32 v5, v6, v6
	s_nop 1
	v_add_f32_dpp v5, v5, v5 quad_perm:[1,0,3,2] row_mask:0xf bank_mask:0xf
	s_nop 1
	v_add_f32_dpp v5, v5, v5 quad_perm:[2,3,0,1] row_mask:0xf bank_mask:0xf
	s_nop 1
	v_add_f32_dpp v5, v5, v5 row_half_mirror row_mask:0xf bank_mask:0xf
	s_nop 1
	v_add_f32_dpp v5, v5, v5 row_mirror row_mask:0xf bank_mask:0xf
	s_nop 1
	v_add_f32_dpp v5, v5, v5 row_bcast:15 row_mask:0xa bank_mask:0xf
	s_nop 1
	v_add_f32_dpp v5, v5, v5 row_bcast:31 row_mask:0xc bank_mask:0xf
	s_nop 1
	v_readlane_b32 s58, v5, 63
	s_nop 1
	v_mov_b32_e32 v5, s58
	s_and_saveexec_b64 s[24:25], s[6:7]
	s_cbranch_execz .LBB0_157
; __device__ __forceinline__ void gmlp_fast(KArgs ap, int l, LAS unsigned char* lds, const Ctx cx) {
;     ...
;             const float rstd = 1.0f / sqrtf(wave_sum(s2) * (1.0f / 512.f) + EPS);
;             if (lane == 0) { ST[2 * s] = mean; ST[2 * s + 1] = rstd; } }
	v_fmamk_f32 v5, v5, 0x3b000000, v194
	s_mov_b32 s0, 0xf800000
	v_mul_f32_e32 v6, 0x4f800000, v5
	v_cmp_gt_f32_e32 vcc, s0, v5
	s_nop 1
	v_cndmask_b32_e32 v5, v5, v6, vcc
	v_sqrt_f32_e32 v6, v5
	s_nop 0
	v_add_u32_e32 v7, -1, v6
	v_fma_f32 v9, -v7, v6, v5
	v_add_u32_e32 v8, 1, v6
	v_cmp_ge_f32_e64 s[0:1], 0, v9
	s_nop 1
	v_cndmask_b32_e64 v7, v6, v7, s[0:1]
	v_fma_f32 v6, -v8, v6, v5
	v_cmp_lt_f32_e64 s[0:1], 0, v6
	s_nop 1
	v_cndmask_b32_e64 v6, v7, v8, s[0:1]
	v_mul_f32_e32 v7, 0x37800000, v6
	v_cndmask_b32_e32 v6, v6, v7, vcc
	v_cmp_class_f32_e32 vcc, v5, v195
	s_nop 1
	v_cndmask_b32_e32 v5, v6, v5, vcc
	v_div_scale_f32 v6, s[0:1], v5, v5, 1.0
	v_rcp_f32_e32 v7, v6
	s_lshl_b32 s0, s56, 3
	s_add_i32 s0, s0, 0
	s_add_i32 s0, s0, 0x11030
	v_fma_f32 v8, -v6, v7, 1.0
	v_fmac_f32_e32 v7, v8, v7
	v_div_scale_f32 v8, vcc, 1.0, v5, 1.0
	v_mul_f32_e32 v9, v8, v7
	v_fma_f32 v10, -v6, v9, v8
	v_fmac_f32_e32 v9, v10, v7
	v_fma_f32 v6, -v6, v9, v8
	v_div_fmas_f32 v6, v6, v7, v9
	v_div_fixup_f32 v5, v6, v5, 1.0
	v_mov_b32_e32 v6, s0
	ds_write_b64 v6, v[4:5]
; __device__ __forceinline__ void unpack8(const u32x4 w, float* f) { f[0] = bflo(w.x); f[1] = bfhi(w.x); f[2] = bflo(w.y); f[3] = bfhi(w.y); f[4] = bflo(w.z); f[5] = bfhi(w.z); f[6] = bflo(w.w); f[7] = bfhi(w.w); }
; __device__ __forceinline__ void gmlp_fast(KArgs ap, int l, LAS unsigned char* lds, const Ctx cx) {
;     ...
;         for (int j = 0; j < 8; ++j) { const int s = wave * 16 + i0 + j;
;             float v[8]; unpack8(raw[j], v);
;             float sm = 0.f;
; #pragma unroll
;             for (int e = 0; e < 8; ++e) { v[e] = gelu_tanh(v[e]); sm += v[e]; }
;             const float mean = wave_sum(sm) * (1.0f / 512.f);
;             float s2 = 0.f;
; #pragma unroll
;             for (int e = 0; e < 8; ++e) { const float d = v[e] - mean; s2 += d * d; }
;             const float rstd = 1.0f / sqrtf(wave_sum(s2) * (1.0f / 512.f) + EPS);
;             if (lane == 0) { ST[2 * s] = mean; ST[2 * s + 1] = rstd; } }
.LBB0_157:
	s_or_b64 exec, exec, s[24:25]
	s_waitcnt vmcnt(0)
	v_lshlrev_b32_e32 v5, 16, v1
	v_mul_f32_e32 v10, 0x3d372713, v5
	v_mul_f32_e32 v10, v10, v5
	v_fma_f32 v10, v10, v5, v5
	v_mul_f32_e32 v10, 0x3f4c422a, v10
	v_add_f32_e32 v10, v10, v10
	v_mul_f32_e32 v10, 0x3fb8aa3b, v10
	v_exp_f32_e32 v10, v10
	v_lshlrev_b32_e32 v4, 16, v0
	v_and_b32_e32 v0, 0xffff0000, v0
	v_mul_f32_e32 v9, 0x3d372713, v0
	v_and_b32_e32 v1, 0xffff0000, v1
	v_mul_f32_e32 v9, v9, v0
	v_fma_f32 v9, v9, v0, v0
	v_mul_f32_e32 v12, 0.5, v0
	v_add_f32_e32 v0, 1.0, v10
	v_mul_f32_e32 v10, 0x3d372713, v1
	v_mul_f32_e32 v10, v10, v1
	v_fma_f32 v10, v10, v1, v1
	v_mul_f32_e32 v10, 0x3f4c422a, v10
	v_add_f32_e32 v10, v10, v10
	v_mul_f32_e32 v10, 0x3fb8aa3b, v10
	v_exp_f32_e32 v10, v10
	v_rcp_f32_e32 v0, v0
	s_waitcnt lgkmcnt(0)
	v_lshlrev_b32_e32 v6, 16, v2
	v_and_b32_e32 v2, 0xffff0000, v2
	v_add_f32_e32 v10, 1.0, v10
	v_rcp_f32_e32 v10, v10
	v_fma_f32 v0, v0, -2.0, 1.0
	v_add_f32_e32 v13, 1.0, v0
	v_mul_f32_e32 v7, 0x3d372713, v4
	v_fma_f32 v0, v10, -2.0, 1.0
	v_mul_f32_e32 v10, 0x3d372713, v6
	v_mul_f32_e32 v10, v10, v6
	v_fma_f32 v10, v10, v6, v6
	v_mul_f32_e32 v10, 0x3f4c422a, v10
	v_add_f32_e32 v10, v10, v10
	v_mul_f32_e32 v10, 0x3fb8aa3b, v10
	v_exp_f32_e32 v10, v10
	v_add_f32_e32 v14, 1.0, v0
	v_mul_f32_e32 v7, v7, v4
	v_lshlrev_b32_e32 v8, 16, v3
	v_add_f32_e32 v0, 1.0, v10
	v_mul_f32_e32 v10, 0x3d372713, v2
	v_mul_f32_e32 v10, v10, v2
	v_fma_f32 v10, v10, v2, v2
	v_mul_f32_e32 v10, 0x3f4c422a, v10
	v_add_f32_e32 v10, v10, v10
	v_rcp_f32_e32 v0, v0
	v_mul_f32_e32 v10, 0x3fb8aa3b, v10
	v_exp_f32_e32 v10, v10
	v_fma_f32 v7, v7, v4, v4
	v_fma_f32 v0, v0, -2.0, 1.0
	v_add_f32_e32 v15, 1.0, v0
	v_add_f32_e32 v0, 1.0, v10
	v_mul_f32_e32 v10, 0x3d372713, v8
	v_mul_f32_e32 v7, 0x3f4c422a, v7
	v_mul_f32_e32 v10, v10, v8
	v_add_f32_e32 v7, v7, v7
	v_mul_f32_e32 v9, 0x3f4c422a, v9
	v_fma_f32 v10, v10, v8, v8
	v_mul_f32_e32 v7, 0x3fb8aa3b, v7
	v_add_f32_e32 v9, v9, v9
	v_mul_f32_e32 v10, 0x3f4c422a, v10
	v_exp_f32_e32 v7, v7
	v_and_b32_e32 v3, 0xffff0000, v3
	v_mul_f32_e32 v9, 0x3fb8aa3b, v9
	v_add_f32_e32 v10, v10, v10
	v_exp_f32_e32 v9, v9
	v_mul_f32_e32 v10, 0x3fb8aa3b, v10
	v_mul_f32_e32 v16, 0x3d372713, v3
	v_exp_f32_e32 v10, v10
	v_mul_f32_e32 v16, v16, v3
	v_fma_f32 v16, v16, v3, v3
	v_add_f32_e32 v7, 1.0, v7
	v_mul_f32_e32 v16, 0x3f4c422a, v16
	v_rcp_f32_e32 v7, v7
	v_add_f32_e32 v9, 1.0, v9
	v_add_f32_e32 v16, v16, v16
	v_rcp_f32_e32 v9, v9
	v_rcp_f32_e32 v0, v0
	v_add_f32_e32 v10, 1.0, v10
	v_mul_f32_e32 v16, 0x3fb8aa3b, v16
	v_rcp_f32_e32 v10, v10
	v_exp_f32_e32 v16, v16
	v_fma_f32 v7, v7, -2.0, 1.0
	v_mul_f32_e32 v4, 0.5, v4
	v_add_f32_e32 v7, 1.0, v7
	v_fma_f32 v9, v9, -2.0, 1.0
	v_fma_f32 v0, v0, -2.0, 1.0
	v_fma_f32 v11, v4, v7, 0
	v_add_f32_e32 v9, 1.0, v9
	v_add_f32_e32 v17, 1.0, v0
	v_fma_f32 v0, v10, -2.0, 1.0
	v_add_f32_e32 v10, 1.0, v16
	v_fmac_f32_e32 v11, v12, v9
	v_mul_f32_e32 v5, 0.5, v5
	v_rcp_f32_e32 v10, v10
	v_fmac_f32_e32 v11, v5, v13
	v_mul_f32_e32 v1, 0.5, v1
	v_fmac_f32_e32 v11, v1, v14
	v_mul_f32_e32 v6, 0.5, v6
	v_fmac_f32_e32 v11, v6, v15
	v_mul_f32_e32 v2, 0.5, v2
	v_fmac_f32_e32 v11, v2, v17
	v_mul_f32_e32 v8, 0.5, v8
	v_add_f32_e32 v16, 1.0, v0
	v_fma_f32 v0, v10, -2.0, 1.0
	v_fmac_f32_e32 v11, v8, v16
	v_mul_f32_e32 v3, 0.5, v3
	v_add_f32_e32 v10, 1.0, v0
	v_fmac_f32_e32 v11, v3, v10
	s_nop 1
	v_add_f32_dpp v0, v11, v11 quad_perm:[1,0,3,2] row_mask:0xf bank_mask:0xf
	s_nop 1
	v_add_f32_dpp v0, v0, v0 quad_perm:[2,3,0,1] row_mask:0xf bank_mask:0xf
	s_nop 1
	v_add_f32_dpp v0, v0, v0 row_half_mirror row_mask:0xf bank_mask:0xf
	s_nop 1
	v_add_f32_dpp v0, v0, v0 row_mirror row_mask:0xf bank_mask:0xf
	s_nop 1
	v_add_f32_dpp v0, v0, v0 row_bcast:15 row_mask:0xa bank_mask:0xf
	s_nop 1
	v_add_f32_dpp v0, v0, v0 row_bcast:31 row_mask:0xc bank_mask:0xf
	s_nop 1
	v_readlane_b32 s58, v0, 63
	s_nop 1
	v_mov_b32_e32 v0, s58
	v_mul_f32_e32 v0, 0x3b000000, v0
	v_fma_f32 v4, v4, v7, -v0
	v_fma_f32 v7, v12, v9, -v0
	v_mul_f32_e32 v7, v7, v7
	v_fmac_f32_e32 v7, v4, v4
	v_fma_f32 v4, v5, v13, -v0
	v_fmac_f32_e32 v7, v4, v4
	v_fma_f32 v1, v1, v14, -v0
	v_fmac_f32_e32 v7, v1, v1
	v_fma_f32 v1, v6, v15, -v0
	v_fmac_f32_e32 v7, v1, v1
	v_fma_f32 v1, v2, v17, -v0
	v_fmac_f32_e32 v7, v1, v1
	v_fma_f32 v1, v8, v16, -v0
	v_fmac_f32_e32 v7, v1, v1
	v_fma_f32 v1, v3, v10, -v0
	v_fmac_f32_e32 v7, v1, v1
	s_nop 1
	v_add_f32_dpp v1, v7, v7 quad_perm:[1,0,3,2] row_mask:0xf bank_mask:0xf
	s_nop 1
	v_add_f32_dpp v1, v1, v1 quad_perm:[2,3,0,1] row_mask:0xf bank_mask:0xf
	s_nop 1
	v_add_f32_dpp v1, v1, v1 row_half_mirror row_mask:0xf bank_mask:0xf
	s_nop 1
	v_add_f32_dpp v1, v1, v1 row_mirror row_mask:0xf bank_mask:0xf
	s_nop 1
	v_add_f32_dpp v1, v1, v1 row_bcast:15 row_mask:0xa bank_mask:0xf
	s_nop 1
	v_add_f32_dpp v1, v1, v1 row_bcast:31 row_mask:0xc bank_mask:0xf
	s_nop 1
	v_readlane_b32 s58, v1, 63
	s_nop 1
	v_mov_b32_e32 v1, s58
	s_and_saveexec_b64 s[24:25], s[6:7]
	s_cbranch_execz .LBB0_142
	v_fmamk_f32 v1, v1, 0x3b000000, v194
	s_mov_b32 s0, 0xf800000
	v_mul_f32_e32 v2, 0x4f800000, v1
	v_cmp_gt_f32_e32 vcc, s0, v1
	s_nop 1
	v_cndmask_b32_e32 v1, v1, v2, vcc
	v_sqrt_f32_e32 v2, v1
	s_nop 0
	v_add_u32_e32 v3, -1, v2
	v_fma_f32 v5, -v3, v2, v1
	v_add_u32_e32 v4, 1, v2
	v_cmp_ge_f32_e64 s[0:1], 0, v5
	s_nop 1
	v_cndmask_b32_e64 v3, v2, v3, s[0:1]
	v_fma_f32 v2, -v4, v2, v1
	v_cmp_lt_f32_e64 s[0:1], 0, v2
	s_nop 1
	v_cndmask_b32_e64 v2, v3, v4, s[0:1]
	v_mul_f32_e32 v3, 0x37800000, v2
	v_cndmask_b32_e32 v2, v2, v3, vcc
	v_cmp_class_f32_e32 vcc, v1, v195
	s_nop 1
	v_cndmask_b32_e32 v1, v2, v1, vcc
	v_div_scale_f32 v2, s[0:1], v1, v1, 1.0
	v_rcp_f32_e32 v3, v2
	s_lshl_b32 s0, s56, 3
	s_add_i32 s0, s0, 0
	s_add_i32 s0, s0, 0x11038
	v_fma_f32 v4, -v2, v3, 1.0
	v_fmac_f32_e32 v3, v4, v3
	v_div_scale_f32 v4, vcc, 1.0, v1, 1.0
	v_mul_f32_e32 v5, v4, v3
	v_fma_f32 v6, -v2, v5, v4
	v_fmac_f32_e32 v5, v6, v3
	v_fma_f32 v2, -v2, v5, v4
	v_div_fmas_f32 v2, v2, v3, v5
	v_div_fixup_f32 v1, v2, v1, 1.0
	v_mov_b32_e32 v2, s0
	ds_write_b64 v2, v[0:1]
	s_branch .LBB0_142

; #define LAS __attribute__((address_space(3)))
; #define MFMA32(a_, b_, c_) __builtin_amdgcn_mfma_f32_32x32x16_bf16((a_), (b_), (c_), 0, 0, 0)
; __device__ __forceinline__ int crow(int reg, int h) { return (reg & 3) + 8 * (reg >> 2) + 4 * h; }
; #define WAVE_FENCE() asm volatile("s_waitcnt lgkmcnt(0)" ::: "memory")
; template <bool OUT>
; __device__ __forceinline__ void ssm_fast(KArgs ap, int l, LAS unsigned char* lds, const Ctx cx) {
;     ...
;             const size_t tk = tok0 + sc * 32;
;             const bf16x8 uf = *(const bf16x8*)(z + (tk + r) * DIN + ZS + g * 16 + 8 * hh);
;             bf16_t uv[2][4];
;             if (OUT) {
; #pragma unroll
;                 for (int tbk = 0; tbk < 2; ++tbk)
; #pragma unroll
;                     for (int j = 0; j < 4; ++j) uv[tbk][j] = z[(tk + tbk * 16 + 4 * (lane >> 4) + j) * DIN + ZS + g * 16 + (lane & 15)];
;             }
;             WAVE_FENCE();
; #pragma unroll
;             for (int nb = 0; nb < 4; ++nb) { f32x16 c;
; #pragma unroll
;                 for (int i = 0; i < 16; ++i) c[i] = 0.f;
;                 c = MFMA32(uf, bt[nb], c);
; #pragma unroll
;                 for (int i = 0; i < 16; ++i) *(LAS float*)(BU + (crow(i, hh) * 128 + nb * 32 + r) * 4) = c[i]; }
.LBB0_170:
	s_lshl_b32 s76, s5, 5
	v_lshl_add_u64 v[0:1], v[90:91], 0, s[76:77]
	v_mov_b64_e32 v[2:3], s[0:1]
	s_movk_i32 s7, 0x1600
	v_mad_u64_u32 v[2:3], s[10:11], v0, s7, v[2:3]
	v_mad_i32_i24 v3, v1, s7, v3
	s_mov_b32 s7, s77
	v_lshl_add_u64 v[0:1], v[2:3], 0, s[6:7]
	v_lshl_add_u64 v[0:1], v[84:85], 1, v[0:1]
	v_add_co_u32_e32 v0, vcc, 0x13000000, v0
	s_nop 0
	v_addc_co_u32_e32 v1, vcc, 0, v1, vcc
	s_cmp_lg_u32 s5, 0
	s_cbranch_scc1 .Lssma_have_u
	global_load_dwordx4 v[102:105], v[0:1], off offset:2560
.Lssma_have_u:
	v_lshl_add_u64 v[106:107], v[0:1], 0, s[58:59]
	s_waitcnt lgkmcnt(0)
	s_mov_b32 s7, 0
	s_waitcnt vmcnt(0)
	v_mfma_f32_32x32x16_bf16 v[0:15], v[102:105], v[64:67], 0
	v_mfma_f32_32x32x16_bf16 v[16:31], v[102:105], v[68:71], 0
	v_mfma_f32_32x32x16_bf16 v[32:47], v[102:105], v[72:75], 0
	v_mfma_f32_32x32x16_bf16 v[48:63], v[102:105], v[76:79], 0
	s_nop 9
	s_cmp_eq_u32 s5, 3
	s_cbranch_scc1 .Lssma_no_pf
	global_load_dwordx4 v[102:105], v[106:107], off offset:2560

; #define LAS __attribute__((address_space(3)))
; #define MFMA32(a_, b_, c_) __builtin_amdgcn_mfma_f32_32x32x16_bf16((a_), (b_), (c_), 0, 0, 0)
; __device__ __forceinline__ int crow(int reg, int h) { return (reg & 3) + 8 * (reg >> 2) + 4 * h; }
; #define WAVE_FENCE() asm volatile("s_waitcnt lgkmcnt(0)" ::: "memory")
; template <bool OUT>
; __device__ __forceinline__ void ssm_fast(KArgs ap, int l, LAS unsigned char* lds, const Ctx cx) {
;     ...
;             const bf16x8 uf = *(const bf16x8*)(z + (tk + r) * DIN + ZS + g * 16 + 8 * hh);
;             bf16_t uv[2][4];
;             if (OUT) {
; #pragma unroll
;                 for (int tbk = 0; tbk < 2; ++tbk)
; #pragma unroll
;                     for (int j = 0; j < 4; ++j) uv[tbk][j] = z[(tk + tbk * 16 + 4 * (lane >> 4) + j) * DIN + ZS + g * 16 + (lane & 15)];
;             }
;             WAVE_FENCE();
; #pragma unroll
;             for (int nb = 0; nb < 4; ++nb) { f32x16 c;
; #pragma unroll
;                 for (int i = 0; i < 16; ++i) c[i] = 0.f;
;                 c = MFMA32(uf, bt[nb], c);
; #pragma unroll
;                 for (int i = 0; i < 16; ++i) *(LAS float*)(BU + (crow(i, hh) * 128 + nb * 32 + r) * 4) = c[i]; }
.Lssmc_have_u:
	v_lshl_add_u64 v[174:175], v[0:1], 0, s[58:59]
	v_or_b32_e32 v0, s8, v100
	v_or_b32_e32 v1, s8, v106
	v_or_b32_e32 v2, s8, v108
	v_or_b32_e32 v3, s8, v110
	v_or_b32_e32 v4, s8, v112
	v_or_b32_e32 v5, s8, v114
	v_or_b32_e32 v6, s8, v116
	v_or_b32_e32 v7, s8, v118
	v_mad_u64_u32 v[32:33], s[10:11], v0, s12, v[140:141]
	v_mad_u64_u32 v[34:35], s[10:11], v1, s12, v[140:141]
	v_mad_u64_u32 v[36:37], s[10:11], v2, s12, v[140:141]
	v_mad_u64_u32 v[38:39], s[10:11], v3, s12, v[140:141]
	v_mad_u64_u32 v[40:41], s[10:11], v4, s12, v[140:141]
	v_mad_u64_u32 v[42:43], s[10:11], v5, s12, v[140:141]
	v_mad_u64_u32 v[44:45], s[10:11], v6, s12, v[140:141]
	v_mad_u64_u32 v[46:47], s[10:11], v7, s12, v[140:141]
	v_mad_i32_i24 v33, s9, v198, v33
	v_mad_i32_i24 v35, s9, v198, v35
	v_mad_i32_i24 v37, s9, v198, v37
	v_mad_i32_i24 v39, s9, v198, v39
	v_mad_i32_i24 v41, s9, v198, v41
	v_mad_i32_i24 v43, s9, v198, v43
	v_mad_i32_i24 v45, s9, v198, v45
	v_mad_i32_i24 v47, s9, v198, v47
	global_load_ushort v144, v[32:33], off offset:2560
	global_load_ushort v131, v[34:35], off offset:2560
	global_load_ushort v129, v[36:37], off offset:2560
	global_load_ushort v127, v[38:39], off offset:2560
	global_load_ushort v125, v[40:41], off offset:2560
	global_load_ushort v123, v[42:43], off offset:2560
	global_load_ushort v121, v[44:45], off offset:2560
	global_load_ushort v119, v[46:47], off offset:2560
	s_waitcnt lgkmcnt(0)
	s_movk_i32 s10, 0xc000
	s_mov_b32 s11, 3
	s_waitcnt vmcnt(8)
	v_mfma_f32_32x32x16_bf16 v[0:15], v[170:173], v[80:83], 0
	v_mfma_f32_32x32x16_bf16 v[16:31], v[170:173], v[64:67], 0
	v_mfma_f32_32x32x16_bf16 v[32:47], v[170:173], v[68:71], 0
	v_mfma_f32_32x32x16_bf16 v[48:63], v[170:173], v[72:75], 0
	s_nop 9
	s_cmp_eq_u32 s1, 3
	s_cbranch_scc1 .Lssmc_no_pf
	global_load_dwordx4 v[170:173], v[174:175], off offset:2560

; #define PG8_BAR __builtin_amdgcn_s_barrier()
; template <class Epi, class Sched>
; __device__ __forceinline__ void gemm_phase(const int tid, LAS unsigned char* lds, const Gemm g, const Sched& S, const Epi& E) {
;     ...
;         const bool has_next = S.next(ui + 1, nxt);
;         const char* nA = has_next ? (const char*)g.A + (size_t)nxt.pm * tstep : cA; const char* nB = has_next ? (const char*)g.Bt + (size_t)nxt.pn * tstep : cB;
;         for (int t = 0; t < nt; t += 2) {
;             const bool last = (t == nt - 2);
;             const char* a1 = cA + (size_t)(t + 1) * kstep;
;             const char* a2 = last ? nA : cA + (size_t)(t + 2) * kstep; const char* b2 = last ? nB : cB + (size_t)(t + 2) * kstep;
;             const char* a3 = a2 + kstep; const char* b3 = b2 + kstep;
;             if (last && has_next) S.a_ready(nxt);
;             PG8_LDB(B0, 0, 0); PG8_LDB(B1, 0, 1); PG8_SCHED; PG8_LDA(At, 0, 0); PG8_STAGE(PG8_SA(1, 1), a1 + hstep, voffA);
;             PG8_WAIT_V(8); PG8_WAIT_L(0); PG8_BAR; PG8_MMA(0, 0, At, B0); PG8_MMA(0, 1, At, B1); PG8_BAR; PG8_SCHED;
;             PG8_LDA(At, 0, 1); PG8_STAGE(PG8_SB(0, 0), b2, voffB); PG8_STAGE(PG8_SB(0, 1), b2 + hstep, voffB); PG8_STAGE(PG8_SA(0, 0), a2, voffA);
;             PG8_WAIT_V(8); PG8_WAIT_L(0); PG8_BAR; PG8_MMA(1, 0, At, B0); PG8_MMA(1, 1, At, B1); PG8_BAR; PG8_SCHED;
;             PG8_LDB(B0, 1, 0); PG8_LDB(B1, 1, 1); PG8_SCHED; PG8_LDA(At, 1, 0); PG8_STAGE(PG8_SA(0, 1), a2 + hstep, voffA);
;             PG8_WAIT_V(8); PG8_WAIT_L(0); PG8_BAR; PG8_MMA(0, 0, At, B0); PG8_MMA(0, 1, At, B1); PG8_BAR; PG8_SCHED;
;             PG8_LDA(At, 1, 1); PG8_STAGE(PG8_SB(1, 0), b3, voffB); PG8_STAGE(PG8_SB(1, 1), b3 + hstep, voffB); PG8_STAGE(PG8_SA(1, 0), a3, voffA);
;             PG8_WAIT_V(8); PG8_WAIT_L(0); PG8_BAR; PG8_MMA(1, 0, At, B0); PG8_MMA(1, 1, At, B1); PG8_BAR; PG8_SCHED;
;         }
;         if (wr == 0) PG8_BAR;
;         asm volatile("s_nop 7\n\ts_nop 7" ::: "memory");
;         E(acc, cur, wr, wc, fr, fq); S.done(cur);
;         if (!has_next) break;
; #pragma unroll
;         for (int a = 0; a < 2; ++a)
; #pragma unroll
;             for (int b = 0; b < 2; ++b)
; #pragma unroll
;                 for (int m = 0; m < 4; ++m)
; #pragma unroll
;                     for (int n = 0; n < 2; ++n) acc[a][b][m][n] = (f32x4){0.f, 0.f, 0.f, 0.f};
;         cur = nxt; cA = nA; cB = nB; ++ui;
.LBB0_394:
	s_ashr_i32 s15, s14, 31
	s_lshl_b64 s[16:17], s[14:15], 18
	s_add_u32 s16, s40, s16
	s_addc_u32 s17, s41, s17
	s_and_b64 s[18:19], s[0:1], exec
	s_cselect_b32 s15, s17, s23
	s_cselect_b32 s66, s16, s22
	s_ashr_i32 s13, s12, 31
	s_lshl_b64 s[18:19], s[12:13], 18
	s_add_u32 s18, s38, s18
	s_addc_u32 s19, s39, s19
	s_and_b64 s[26:27], s[0:1], exec
	s_cselect_b32 s13, s19, s25
	s_cselect_b32 s67, s18, s24
	s_add_u32 s22, s22, 0x20080
	s_addc_u32 s23, s23, 0
	s_add_u32 s68, s24, 0x100
	v_mov_b32_e32 v0, 0
	s_addc_u32 s69, s25, 0
	s_mov_b32 s70, -2
	v_mov_b32_e32 v1, 0
	v_mov_b64_e32 v[2:3], 0
	v_mov_b64_e32 v[4:5], 0
	v_mov_b64_e32 v[6:7], 0
	v_mov_b64_e32 v[8:9], 0
	v_mov_b64_e32 v[10:11], 0
	v_mov_b64_e32 v[12:13], 0
	v_mov_b64_e32 v[14:15], 0
	v_mov_b64_e32 v[16:17], 0
	v_mov_b64_e32 v[18:19], 0
	v_mov_b64_e32 v[20:21], 0
	v_mov_b64_e32 v[22:23], 0
	v_mov_b64_e32 v[24:25], 0
	v_mov_b64_e32 v[26:27], 0
	v_mov_b64_e32 v[28:29], 0
	v_mov_b64_e32 v[30:31], 0
	v_mov_b64_e32 v[32:33], 0
	v_mov_b64_e32 v[34:35], 0
	v_mov_b64_e32 v[36:37], 0
	v_mov_b64_e32 v[38:39], 0
	v_mov_b64_e32 v[40:41], 0
	v_mov_b64_e32 v[42:43], 0
	v_mov_b64_e32 v[44:45], 0
	v_mov_b64_e32 v[46:47], 0
	v_mov_b64_e32 v[48:49], 0
	v_mov_b64_e32 v[50:51], 0
	v_mov_b64_e32 v[52:53], 0
	v_mov_b64_e32 v[54:55], 0
	v_mov_b64_e32 v[56:57], 0
	v_mov_b64_e32 v[58:59], 0
	v_mov_b64_e32 v[60:61], 0
	v_mov_b64_e32 v[62:63], 0
	v_mov_b64_e32 v[64:65], 0
	v_mov_b64_e32 v[66:67], 0
	v_mov_b64_e32 v[68:69], 0
	v_mov_b64_e32 v[70:71], 0
	v_mov_b64_e32 v[72:73], 0
	v_mov_b64_e32 v[74:75], 0
	v_mov_b64_e32 v[76:77], 0
	v_mov_b64_e32 v[78:79], 0
	v_mov_b64_e32 v[80:81], 0
	v_mov_b64_e32 v[82:83], 0
	v_mov_b64_e32 v[84:85], 0
	v_mov_b64_e32 v[86:87], 0
	v_mov_b64_e32 v[88:89], 0
	v_mov_b64_e32 v[90:91], 0
	v_mov_b64_e32 v[92:93], 0
	v_mov_b64_e32 v[94:95], 0
	v_mov_b64_e32 v[96:97], 0
	v_mov_b64_e32 v[98:99], 0
	v_mov_b64_e32 v[100:101], 0
	v_mov_b64_e32 v[102:103], 0
	v_mov_b64_e32 v[104:105], 0
	v_mov_b64_e32 v[106:107], 0
	v_mov_b64_e32 v[108:109], 0
	v_mov_b64_e32 v[110:111], 0
	v_mov_b64_e32 v[112:113], 0
	v_mov_b64_e32 v[114:115], 0
	v_mov_b64_e32 v[116:117], 0
	v_mov_b64_e32 v[118:119], 0
	v_mov_b64_e32 v[120:121], 0
	v_mov_b64_e32 v[122:123], 0
	v_mov_b64_e32 v[124:125], 0
	v_mov_b64_e32 v[126:127], 0

; #define PG8_BAR __builtin_amdgcn_s_barrier()
; template <class Epi, class Sched>
; __device__ __forceinline__ void gemm_phase(const int tid, LAS unsigned char* lds, const Gemm g, const Sched& S, const Epi& E) {
;     ...
;         const bool has_next = S.next(ui + 1, nxt);
;         const char* nA = has_next ? (const char*)g.A + (size_t)nxt.pm * tstep : cA; const char* nB = has_next ? (const char*)g.Bt + (size_t)nxt.pn * tstep : cB;
;         for (int t = 0; t < nt; t += 2) {
;             const bool last = (t == nt - 2);
;             const char* a1 = cA + (size_t)(t + 1) * kstep;
;             const char* a2 = last ? nA : cA + (size_t)(t + 2) * kstep; const char* b2 = last ? nB : cB + (size_t)(t + 2) * kstep;
;             const char* a3 = a2 + kstep; const char* b3 = b2 + kstep;
;             if (last && has_next) S.a_ready(nxt);
;             PG8_LDB(B0, 0, 0); PG8_LDB(B1, 0, 1); PG8_SCHED; PG8_LDA(At, 0, 0); PG8_STAGE(PG8_SA(1, 1), a1 + hstep, voffA);
;             PG8_WAIT_V(8); PG8_WAIT_L(0); PG8_BAR; PG8_MMA(0, 0, At, B0); PG8_MMA(0, 1, At, B1); PG8_BAR; PG8_SCHED;
;             PG8_LDA(At, 0, 1); PG8_STAGE(PG8_SB(0, 0), b2, voffB); PG8_STAGE(PG8_SB(0, 1), b2 + hstep, voffB); PG8_STAGE(PG8_SA(0, 0), a2, voffA);
;             PG8_WAIT_V(8); PG8_WAIT_L(0); PG8_BAR; PG8_MMA(1, 0, At, B0); PG8_MMA(1, 1, At, B1); PG8_BAR; PG8_SCHED;
;             PG8_LDB(B0, 1, 0); PG8_LDB(B1, 1, 1); PG8_SCHED; PG8_LDA(At, 1, 0); PG8_STAGE(PG8_SA(0, 1), a2 + hstep, voffA);
;             PG8_WAIT_V(8); PG8_WAIT_L(0); PG8_BAR; PG8_MMA(0, 0, At, B0); PG8_MMA(0, 1, At, B1); PG8_BAR; PG8_SCHED;
;             PG8_LDA(At, 1, 1); PG8_STAGE(PG8_SB(1, 0), b3, voffB); PG8_STAGE(PG8_SB(1, 1), b3 + hstep, voffB); PG8_STAGE(PG8_SA(1, 0), a3, voffA);
;             PG8_WAIT_V(8); PG8_WAIT_L(0); PG8_BAR; PG8_MMA(1, 0, At, B0); PG8_MMA(1, 1, At, B1); PG8_BAR; PG8_SCHED;
;         }
;         if (wr == 0) PG8_BAR;
;         asm volatile("s_nop 7\n\ts_nop 7" ::: "memory");
;         E(acc, cur, wr, wc, fr, fq); S.done(cur);
;         if (!has_next) break;
; #pragma unroll
;         for (int a = 0; a < 2; ++a)
; #pragma unroll
;             for (int b = 0; b < 2; ++b)
; #pragma unroll
;                 for (int m = 0; m < 4; ++m)
; #pragma unroll
;                     for (int n = 0; n < 2; ++n) acc[a][b][m][n] = (f32x4){0.f, 0.f, 0.f, 0.f};
;         cur = nxt; cA = nA; cB = nB; ++ui;
.LBB0_549:
	s_ashr_i32 s17, s16, 31
	s_lshl_b64 s[18:19], s[16:17], 20
	s_add_u32 s18, s41, s18
	s_addc_u32 s19, s55, s19
	s_and_b64 s[20:21], s[0:1], exec
	s_cselect_b32 s5, s19, s25
	s_cselect_b32 s17, s18, s24
	s_ashr_i32 s15, s14, 31
	s_lshl_b64 s[20:21], s[14:15], 20
	s_add_u32 s20, s39, s20
	s_addc_u32 s21, s40, s21
	s_and_b64 s[28:29], s[0:1], exec
	s_cselect_b32 s15, s21, s27
	s_cselect_b32 s23, s20, s26
	s_add_u32 s24, s24, 0x80080
	s_addc_u32 s25, s25, 0
	s_add_u32 s69, s26, 0x100
	v_mov_b32_e32 v0, 0
	s_addc_u32 s70, s27, 0
	s_mov_b32 s71, -2
	s_waitcnt lgkmcnt(0)
	v_mov_b32_e32 v1, 0
	v_mov_b64_e32 v[2:3], 0
	v_mov_b64_e32 v[4:5], 0
	v_mov_b64_e32 v[6:7], 0
	v_mov_b64_e32 v[8:9], 0
	v_mov_b64_e32 v[10:11], 0
	v_mov_b64_e32 v[12:13], 0
	v_mov_b64_e32 v[14:15], 0
	v_mov_b64_e32 v[16:17], 0
	v_mov_b64_e32 v[18:19], 0
	v_mov_b64_e32 v[20:21], 0
	v_mov_b64_e32 v[22:23], 0
	v_mov_b64_e32 v[24:25], 0
	v_mov_b64_e32 v[26:27], 0
	v_mov_b64_e32 v[28:29], 0
	v_mov_b64_e32 v[30:31], 0
	v_mov_b64_e32 v[32:33], 0
	v_mov_b64_e32 v[34:35], 0
	v_mov_b64_e32 v[36:37], 0
	v_mov_b64_e32 v[38:39], 0
	v_mov_b64_e32 v[40:41], 0
	v_mov_b64_e32 v[42:43], 0
	v_mov_b64_e32 v[44:45], 0
	v_mov_b64_e32 v[46:47], 0
	v_mov_b64_e32 v[48:49], 0
	v_mov_b64_e32 v[50:51], 0
	v_mov_b64_e32 v[52:53], 0
	v_mov_b64_e32 v[54:55], 0
	v_mov_b64_e32 v[56:57], 0
	v_mov_b64_e32 v[58:59], 0
	v_mov_b64_e32 v[60:61], 0
	v_mov_b64_e32 v[62:63], 0
	v_mov_b64_e32 v[64:65], 0
	v_mov_b64_e32 v[66:67], 0
	v_mov_b64_e32 v[68:69], 0
	v_mov_b64_e32 v[70:71], 0
	v_mov_b64_e32 v[72:73], 0
	v_mov_b64_e32 v[74:75], 0
	v_mov_b64_e32 v[76:77], 0
	v_mov_b64_e32 v[78:79], 0
	v_mov_b64_e32 v[80:81], 0
	v_mov_b64_e32 v[82:83], 0
	v_mov_b64_e32 v[84:85], 0
	v_mov_b64_e32 v[86:87], 0
	v_mov_b64_e32 v[88:89], 0
	v_mov_b64_e32 v[90:91], 0
	v_mov_b64_e32 v[92:93], 0
	v_mov_b64_e32 v[94:95], 0
	v_mov_b64_e32 v[96:97], 0
	v_mov_b64_e32 v[98:99], 0
	v_mov_b64_e32 v[100:101], 0
	v_mov_b64_e32 v[102:103], 0
	v_mov_b64_e32 v[104:105], 0
	v_mov_b64_e32 v[106:107], 0
	v_mov_b64_e32 v[108:109], 0
	v_mov_b64_e32 v[110:111], 0
	v_mov_b64_e32 v[112:113], 0
	v_mov_b64_e32 v[114:115], 0
	v_mov_b64_e32 v[116:117], 0
	v_mov_b64_e32 v[118:119], 0
	v_mov_b64_e32 v[120:121], 0
	v_mov_b64_e32 v[122:123], 0
	v_mov_b64_e32 v[124:125], 0
	v_mov_b64_e32 v[126:127], 0

; #define PG8_BAR __builtin_amdgcn_s_barrier()
; template <class Epi, class Sched>
; __device__ __forceinline__ void gemm_phase(const int tid, LAS unsigned char* lds, const Gemm g, const Sched& S, const Epi& E) {
;     ...
;         const bool has_next = S.next(ui + 1, nxt);
;         const char* nA = has_next ? (const char*)g.A + (size_t)nxt.pm * tstep : cA; const char* nB = has_next ? (const char*)g.Bt + (size_t)nxt.pn * tstep : cB;
;         for (int t = 0; t < nt; t += 2) {
;             const bool last = (t == nt - 2);
;             const char* a1 = cA + (size_t)(t + 1) * kstep;
;             const char* a2 = last ? nA : cA + (size_t)(t + 2) * kstep; const char* b2 = last ? nB : cB + (size_t)(t + 2) * kstep;
;             const char* a3 = a2 + kstep; const char* b3 = b2 + kstep;
;             if (last && has_next) S.a_ready(nxt);
;             PG8_LDB(B0, 0, 0); PG8_LDB(B1, 0, 1); PG8_SCHED; PG8_LDA(At, 0, 0); PG8_STAGE(PG8_SA(1, 1), a1 + hstep, voffA);
;             PG8_WAIT_V(8); PG8_WAIT_L(0); PG8_BAR; PG8_MMA(0, 0, At, B0); PG8_MMA(0, 1, At, B1); PG8_BAR; PG8_SCHED;
;             PG8_LDA(At, 0, 1); PG8_STAGE(PG8_SB(0, 0), b2, voffB); PG8_STAGE(PG8_SB(0, 1), b2 + hstep, voffB); PG8_STAGE(PG8_SA(0, 0), a2, voffA);
;             PG8_WAIT_V(8); PG8_WAIT_L(0); PG8_BAR; PG8_MMA(1, 0, At, B0); PG8_MMA(1, 1, At, B1); PG8_BAR; PG8_SCHED;
;             PG8_LDB(B0, 1, 0); PG8_LDB(B1, 1, 1); PG8_SCHED; PG8_LDA(At, 1, 0); PG8_STAGE(PG8_SA(0, 1), a2 + hstep, voffA);
;             PG8_WAIT_V(8); PG8_WAIT_L(0); PG8_BAR; PG8_MMA(0, 0, At, B0); PG8_MMA(0, 1, At, B1); PG8_BAR; PG8_SCHED;
;             PG8_LDA(At, 1, 1); PG8_STAGE(PG8_SB(1, 0), b3, voffB); PG8_STAGE(PG8_SB(1, 1), b3 + hstep, voffB); PG8_STAGE(PG8_SA(1, 0), a3, voffA);
;             PG8_WAIT_V(8); PG8_WAIT_L(0); PG8_BAR; PG8_MMA(1, 0, At, B0); PG8_MMA(1, 1, At, B1); PG8_BAR; PG8_SCHED;
;         }
;         if (wr == 0) PG8_BAR;
;         asm volatile("s_nop 7\n\ts_nop 7" ::: "memory");
;         E(acc, cur, wr, wc, fr, fq); S.done(cur);
;         if (!has_next) break;
; #pragma unroll
;         for (int a = 0; a < 2; ++a)
; #pragma unroll
;             for (int b = 0; b < 2; ++b)
; #pragma unroll
;                 for (int m = 0; m < 4; ++m)
; #pragma unroll
;                     for (int n = 0; n < 2; ++n) acc[a][b][m][n] = (f32x4){0.f, 0.f, 0.f, 0.f};
;         cur = nxt; cA = nA; cB = nB; ++ui;
.LBB0_669:
	s_ashr_i32 s15, s14, 31
	s_lshl_b64 s[16:17], s[14:15], 20
	s_add_u32 s16, s56, s16
	s_addc_u32 s17, s57, s17
	s_and_b64 s[18:19], s[0:1], exec
	s_cselect_b32 s15, s17, s23
	s_cselect_b32 s68, s16, s22
	s_ashr_i32 s13, s12, 31
	s_lshl_b64 s[18:19], s[12:13], 20
	s_add_u32 s18, s41, s18
	s_addc_u32 s19, s55, s19
	s_and_b64 s[26:27], s[0:1], exec
	s_cselect_b32 s13, s19, s25
	s_cselect_b32 s69, s18, s24
	s_add_u32 s22, s22, 0x80080
	s_addc_u32 s23, s23, 0
	s_add_u32 s70, s24, 0x100
	v_mov_b32_e32 v0, 0
	s_addc_u32 s71, s25, 0
	s_mov_b32 s72, -2
	v_mov_b32_e32 v1, 0
	v_mov_b64_e32 v[2:3], 0
	v_mov_b64_e32 v[4:5], 0
	v_mov_b64_e32 v[6:7], 0
	v_mov_b64_e32 v[8:9], 0
	v_mov_b64_e32 v[10:11], 0
	v_mov_b64_e32 v[12:13], 0
	v_mov_b64_e32 v[14:15], 0
	v_mov_b64_e32 v[16:17], 0
	v_mov_b64_e32 v[18:19], 0
	v_mov_b64_e32 v[20:21], 0
	v_mov_b64_e32 v[22:23], 0
	v_mov_b64_e32 v[24:25], 0
	v_mov_b64_e32 v[26:27], 0
	v_mov_b64_e32 v[28:29], 0
	v_mov_b64_e32 v[30:31], 0
	v_mov_b64_e32 v[32:33], 0
	v_mov_b64_e32 v[34:35], 0
	v_mov_b64_e32 v[36:37], 0
	v_mov_b64_e32 v[38:39], 0
	v_mov_b64_e32 v[40:41], 0
	v_mov_b64_e32 v[42:43], 0
	v_mov_b64_e32 v[44:45], 0
	v_mov_b64_e32 v[46:47], 0
	v_mov_b64_e32 v[48:49], 0
	v_mov_b64_e32 v[50:51], 0
	v_mov_b64_e32 v[52:53], 0
	v_mov_b64_e32 v[54:55], 0
	v_mov_b64_e32 v[56:57], 0
	v_mov_b64_e32 v[58:59], 0
	v_mov_b64_e32 v[60:61], 0
	v_mov_b64_e32 v[62:63], 0
	v_mov_b64_e32 v[64:65], 0
	v_mov_b64_e32 v[66:67], 0
	v_mov_b64_e32 v[68:69], 0
	v_mov_b64_e32 v[70:71], 0
	v_mov_b64_e32 v[72:73], 0
	v_mov_b64_e32 v[74:75], 0
	v_mov_b64_e32 v[76:77], 0
	v_mov_b64_e32 v[78:79], 0
	v_mov_b64_e32 v[80:81], 0
	v_mov_b64_e32 v[82:83], 0
	v_mov_b64_e32 v[84:85], 0
	v_mov_b64_e32 v[86:87], 0
	v_mov_b64_e32 v[88:89], 0
	v_mov_b64_e32 v[90:91], 0
	v_mov_b64_e32 v[92:93], 0
	v_mov_b64_e32 v[94:95], 0
	v_mov_b64_e32 v[96:97], 0
	v_mov_b64_e32 v[98:99], 0
	v_mov_b64_e32 v[100:101], 0
	v_mov_b64_e32 v[102:103], 0
	v_mov_b64_e32 v[104:105], 0
	v_mov_b64_e32 v[106:107], 0
	v_mov_b64_e32 v[108:109], 0
	v_mov_b64_e32 v[110:111], 0
	v_mov_b64_e32 v[112:113], 0
	v_mov_b64_e32 v[114:115], 0
	v_mov_b64_e32 v[116:117], 0
	v_mov_b64_e32 v[118:119], 0
	v_mov_b64_e32 v[120:121], 0
	v_mov_b64_e32 v[122:123], 0
	v_mov_b64_e32 v[124:125], 0
	v_mov_b64_e32 v[126:127], 0

; #define PG8_WAIT_V(n) asm volatile("s_waitcnt vmcnt(" #n ")" ::: "memory")
; #define a (*get_args())
; template <class Epi, class Sched>
; __device__ __forceinline__ void gemm_phase(const int tid, LAS unsigned char* lds, const Gemm g, const Sched& S, const Epi& E) {
;     ...
;         const char* nA = has_next ? (const char*)g.A + (size_t)nxt.pm * tstep : cA; const char* nB = has_next ? (const char*)g.Bt + (size_t)nxt.pn * tstep : cB;
;         for (int t = 0; t < nt; t += 2) {
;             const bool last = (t == nt - 2);
;             const char* a1 = cA + (size_t)(t + 1) * kstep;
;             const char* a2 = last ? nA : cA + (size_t)(t + 2) * kstep; const char* b2 = last ? nB : cB + (size_t)(t + 2) * kstep;
;             const char* a3 = a2 + kstep; const char* b3 = b2 + kstep;
;             if (last && has_next) S.a_ready(nxt);
;             PG8_LDB(B0, 0, 0); PG8_LDB(B1, 0, 1); PG8_SCHED; PG8_LDA(At, 0, 0); PG8_STAGE(PG8_SA(1, 1), a1 + hstep, voffA);
;             PG8_WAIT_V(8); PG8_WAIT_L(0); PG8_BAR; PG8_MMA(0, 0, At, B0); PG8_MMA(0, 1, At, B1); PG8_BAR; PG8_SCHED;
;             PG8_LDA(At, 0, 1); PG8_STAGE(PG8_SB(0, 0), b2, voffB); PG8_STAGE(PG8_SB(0, 1), b2 + hstep, voffB); PG8_STAGE(PG8_SA(0, 0), a2, voffA);
;             PG8_WAIT_V(8); PG8_WAIT_L(0); PG8_BAR; PG8_MMA(1, 0, At, B0); PG8_MMA(1, 1, At, B1); PG8_BAR; PG8_SCHED;
;             PG8_LDB(B0, 1, 0); PG8_LDB(B1, 1, 1); PG8_SCHED; PG8_LDA(At, 1, 0); PG8_STAGE(PG8_SA(0, 1), a2 + hstep, voffA);
;             PG8_WAIT_V(8); PG8_WAIT_L(0); PG8_BAR; PG8_MMA(0, 0, At, B0); PG8_MMA(0, 1, At, B1); PG8_BAR; PG8_SCHED;
;             PG8_LDA(At, 1, 1); PG8_STAGE(PG8_SB(1, 0), b3, voffB); PG8_STAGE(PG8_SB(1, 1), b3 + hstep, voffB); PG8_STAGE(PG8_SA(1, 0), a3, voffA);
;             PG8_WAIT_V(8); PG8_WAIT_L(0); PG8_BAR; PG8_MMA(1, 0, At, B0); PG8_MMA(1, 1, At, B1); PG8_BAR; PG8_SCHED;
;         }
;         if (wr == 0) PG8_BAR;
;         asm volatile("s_nop 7\n\ts_nop 7" ::: "memory");
;         E(acc, cur, wr, wc, fr, fq); S.done(cur);
;         if (!has_next) break;
; #pragma unroll
;         for (int a = 0; a < 2; ++a)
; #pragma unroll
;             for (int b = 0; b < 2; ++b)
; #pragma unroll
;                 for (int m = 0; m < 4; ++m)
; #pragma unroll
;                     for (int n = 0; n < 2; ++n) acc[a][b][m][n] = (f32x4){0.f, 0.f, 0.f, 0.f};
;         cur = nxt; cA = nA; cB = nB; ++ui;
.LBB0_762:
	s_add_u32 s67, s20, 0x100
	v_mov_b32_e32 v0, 0
	s_addc_u32 s68, s21, 0
	s_mov_b32 s69, -2
	s_waitcnt lgkmcnt(0)
	v_mov_b32_e32 v1, 0
	v_mov_b64_e32 v[2:3], 0
	v_mov_b64_e32 v[4:5], 0
	v_mov_b64_e32 v[6:7], 0
	v_mov_b64_e32 v[8:9], 0
	v_mov_b64_e32 v[10:11], 0
	v_mov_b64_e32 v[12:13], 0
	v_mov_b64_e32 v[14:15], 0
	v_mov_b64_e32 v[16:17], 0
	v_mov_b64_e32 v[18:19], 0
	v_mov_b64_e32 v[20:21], 0
	v_mov_b64_e32 v[22:23], 0
	v_mov_b64_e32 v[24:25], 0
	v_mov_b64_e32 v[26:27], 0
	v_mov_b64_e32 v[28:29], 0
	v_mov_b64_e32 v[30:31], 0
	v_mov_b64_e32 v[32:33], 0
	v_mov_b64_e32 v[34:35], 0
	v_mov_b64_e32 v[36:37], 0
	v_mov_b64_e32 v[38:39], 0
	v_mov_b64_e32 v[40:41], 0
	v_mov_b64_e32 v[42:43], 0
	v_mov_b64_e32 v[44:45], 0
	v_mov_b64_e32 v[46:47], 0
	v_mov_b64_e32 v[48:49], 0
	v_mov_b64_e32 v[50:51], 0
	v_mov_b64_e32 v[52:53], 0
	v_mov_b64_e32 v[54:55], 0
	v_mov_b64_e32 v[56:57], 0
	v_mov_b64_e32 v[58:59], 0
	v_mov_b64_e32 v[60:61], 0
	v_mov_b64_e32 v[62:63], 0
	v_mov_b64_e32 v[64:65], 0
	v_mov_b64_e32 v[66:67], 0
	v_mov_b64_e32 v[68:69], 0
	v_mov_b64_e32 v[70:71], 0
	v_mov_b64_e32 v[72:73], 0
	v_mov_b64_e32 v[74:75], 0
	v_mov_b64_e32 v[76:77], 0
	v_mov_b64_e32 v[78:79], 0
	v_mov_b64_e32 v[80:81], 0
	v_mov_b64_e32 v[82:83], 0
	v_mov_b64_e32 v[84:85], 0
	v_mov_b64_e32 v[86:87], 0
	v_mov_b64_e32 v[88:89], 0
	v_mov_b64_e32 v[90:91], 0
	v_mov_b64_e32 v[92:93], 0
	v_mov_b64_e32 v[94:95], 0
	v_mov_b64_e32 v[96:97], 0
	v_mov_b64_e32 v[98:99], 0
	v_mov_b64_e32 v[100:101], 0
	v_mov_b64_e32 v[102:103], 0
	v_mov_b64_e32 v[104:105], 0
	v_mov_b64_e32 v[106:107], 0
	v_mov_b64_e32 v[108:109], 0
	v_mov_b64_e32 v[110:111], 0
	v_mov_b64_e32 v[112:113], 0
	v_mov_b64_e32 v[114:115], 0
	v_mov_b64_e32 v[116:117], 0
	v_mov_b64_e32 v[118:119], 0
	v_mov_b64_e32 v[120:121], 0
	v_mov_b64_e32 v[122:123], 0
	v_mov_b64_e32 v[124:125], 0
	v_mov_b64_e32 v[126:127], 0
